# stack2 + counted lgkmcnt waits inside the attention PV MFMA clusters merged into one lgkmcnt(0) (32 satisfied waits deleted)
# baseline (speedup 1.0000x reference)
; template <int MODE> ...
;     ...
;         const LAS unsigned char* Sl = ring + ((t + base) % 3) * SLOT;
; #pragma unroll
;         for (int hf = 0; hf < NH; ++hf) {
;             if (MODE == 1) { const int ks = ktok0 + 64 * t + 32 * hf;
;                 if (ks + 31 < qtok0 - 128 || ks > qtok0 + 31 + 128) continue; }
;             bf16x8 kf[2][2][2];
; #pragma unroll
;             for (int jj = 0; jj < 2; ++jj)
; #pragma unroll
;                 for (int kt = 0; kt < 2; ++kt)
; #pragma unroll
;                     for (int ks = 0; ks < 2; ++ks) kf[jj][kt][ks] = *(const LAS bf16x8*)(Sl + kad[jj][ks] + (32 * hf + 16 * kt) * 128);
;             f32x4 bb[2][2];
; #pragma unroll
;             for (int jj = 0; jj < 2; ++jj) { const LAS f32x4* bl = bcp + ((MODE == 0) ? (dr0 + t - act0) * 8 : 16 * t + 8 * hf) + bofs[jj];
; #pragma unroll
;                 for (int kt = 0; kt < 2; ++kt) bb[jj][kt] = bl[4 * kt]; }
;             s16x4 vlo[2][4], vhi[2][4];
; #pragma unroll
;             for (int jj = 0; jj < 2; ++jj)
; #pragma unroll
;                 for (int dt = 0; dt < 4; ++dt) { const LAS unsigned char* vp = Sl + vad[jj] + (32 * hf) * 128 + ((dt ^ sv) << 5);
;                     vlo[jj][dt] = __builtin_bit_cast(s16x4, __builtin_amdgcn_ds_read_tr16_b64_v4i16((LAS s16x4*)(vp)));
;                     vhi[jj][dt] = __builtin_bit_cast(s16x4, __builtin_amdgcn_ds_read_tr16_b64_v4i16((LAS s16x4*)(vp + 2048))); }
;             __builtin_amdgcn_sched_barrier(0);
;             f32x4 s[2][2];
; #pragma unroll
;             for (int jj = 0; jj < 2; ++jj)
; #pragma unroll
;                 for (int kt = 0; kt < 2; ++kt) { f32x4 a = (MODE == 0) ? bb[jj][kt] + mneg[jj][kt] : bb[jj][kt];
;                     a = __builtin_amdgcn_mfma_f32_16x16x32_bf16(kf[jj][kt][0], qf[jj][0], a, 0, 0, 0);
;                     s[jj][kt] = __builtin_amdgcn_mfma_f32_16x16x32_bf16(kf[jj][kt][1], qf[jj][1], a, 0, 0, 0); }
;             u32x4 pw[2];
; #pragma unroll
;             for (int jj = 0; jj < 2; ++jj) {
;                 const float tm = vmax3(vmax3(s[jj][0][0], s[jj][0][1], s[jj][0][2]), vmax3(s[jj][0][3], s[jj][1][0], s[jj][1][1]), vmax3(s[jj][1][2], s[jj][1][3], s[jj][1][3]));
;                 const float mn = quad_max3(mrun[jj], tm);
;                 const float alpha = __builtin_amdgcn_exp2f(mrun[jj] - mn);
;                 mrun[jj] = mn;
;                 float rsum = 0.f;
.LBB0_278:
	s_sub_i32 s52, s25, s23
	v_lshlrev_b32_e32 v94, 5, v93
	s_add_i32 s0, s23, 7
	v_xor_b32_e32 v95, 32, v94
	v_xor_b32_e32 v96, 64, v94
	s_cmp_gt_u32 s0, 7
	v_xor_b32_e32 v97, 0x60, v94
	s_cbranch_scc1 .LBB0_291
	s_lshl_b32 s0, s86, 14
	s_add_i32 s0, s0, 0
	v_add_u32_e32 v0, s0, v89
	s_lshl_b32 s14, s52, 7
	v_add_u32_e32 v2, s0, v88
	ds_read_b128 v[6:9], v0
	ds_read_b128 v[10:13], v0 offset:2048
	ds_read_b128 v[14:17], v2
	ds_read_b128 v[34:37], v2 offset:2048
	v_add_u32_e32 v0, s0, v92
	s_add_i32 s14, s24, s14
	v_add_u32_e32 v2, s0, v91
	ds_read_b128 v[38:41], v0
	ds_read_b128 v[42:45], v0 offset:2048
	ds_read_b128 v[46:49], v2
	ds_read_b128 v[50:53], v2 offset:2048
	v_lshl_add_u32 v0, v87, 4, s14
	ds_read_b128 v[54:57], v0
	ds_read_b128 v[58:61], v0 offset:64
	v_lshl_add_u32 v0, v90, 4, s14
	ds_read_b128 v[62:65], v0
	ds_read_b128 v[66:69], v0 offset:64
	v_add3_u32 v0, v86, v122, s0
	v_add_u32_e32 v2, v0, v94
	v_add_u32_e32 v3, v0, v95
	ds_read_b64_tr_b16 v[70:71], v2 offset:8192
	ds_read_b64_tr_b16 v[72:73], v2 offset:10240
	ds_read_b64_tr_b16 v[74:75], v3 offset:8192
	ds_read_b64_tr_b16 v[76:77], v3 offset:10240
	v_add_u32_e32 v2, v0, v96
	v_add_u32_e32 v0, v0, v97
	ds_read_b64_tr_b16 v[78:79], v2 offset:8192
	ds_read_b64_tr_b16 v[80:81], v2 offset:10240
	ds_read_b64_tr_b16 v[126:127], v0 offset:8192
	ds_read_b64_tr_b16 v[128:129], v0 offset:10240
	v_add3_u32 v0, v123, v122, s0
	v_add_u32_e32 v2, v0, v94
	v_add_u32_e32 v3, v0, v95
	ds_read_b64_tr_b16 v[130:131], v2 offset:8192
	ds_read_b64_tr_b16 v[132:133], v2 offset:10240
	ds_read_b64_tr_b16 v[134:135], v3 offset:8192
	ds_read_b64_tr_b16 v[136:137], v3 offset:10240
	v_add_u32_e32 v2, v0, v96
	v_add_u32_e32 v0, v0, v97
	ds_read_b64_tr_b16 v[138:139], v2 offset:8192
	ds_read_b64_tr_b16 v[140:141], v2 offset:10240
	ds_read_b64_tr_b16 v[2:3], v0 offset:8192
	ds_read_b64_tr_b16 v[4:5], v0 offset:10240
	s_waitcnt lgkmcnt(14)
	v_pk_add_f32 v[56:57], v[112:113], v[56:57]
	v_pk_add_f32 v[54:55], v[110:111], v[54:55]
	s_mov_b32 s0, 0xf149f2ca
	s_nop 0
	v_mfma_f32_16x16x32_bf16 v[6:9], v[6:9], v[30:33], v[54:57]
	s_nop 2
	v_pk_add_f32 v[56:57], v[114:115], v[60:61]
	v_pk_add_f32 v[54:55], v[108:109], v[58:59]
	v_mfma_f32_16x16x32_bf16 v[6:9], v[14:17], v[26:29], v[6:9]
	v_pk_add_f32 v[16:17], v[106:107], v[64:65]
	v_pk_add_f32 v[14:15], v[102:103], v[62:63]
	v_mfma_f32_16x16x32_bf16 v[10:13], v[10:13], v[30:33], v[54:57]
	v_mfma_f32_16x16x32_bf16 v[10:13], v[34:37], v[26:29], v[10:13]
	s_nop 2
	v_maximum3_f32 v0, v6, v7, v8
	v_pk_add_f32 v[56:57], v[104:105], v[68:69]
	v_pk_add_f32 v[54:55], v[100:101], v[66:67]
	v_mfma_f32_16x16x32_bf16 v[14:17], v[38:41], v[22:25], v[14:17]
	v_mfma_f32_16x16x32_bf16 v[14:17], v[46:49], v[18:21], v[14:17]
	v_maximum3_f32 v34, v9, v10, v11
	v_maximum3_f32 v35, v12, v13, v13
	v_maximum3_f32 v0, v0, v34, v35
	v_mov_b32_e32 v34, v0
	s_nop 1
	v_permlane16_swap_b32_e32 v0, v34
	v_maximum3_f32 v0, v0, v34, v34
	v_mov_b32_e32 v34, v0
	s_nop 1
	v_permlane32_swap_b32_e32 v0, v34
	v_maximum3_f32 v125, v0, s0, v34
	v_mfma_f32_16x16x32_bf16 v[34:37], v[42:45], v[22:25], v[54:57]
	v_sub_f32_e32 v6, v6, v125
	v_exp_f32_e32 v38, v6
	v_sub_f32_e32 v6, v7, v125
	v_mfma_f32_16x16x32_bf16 v[34:37], v[50:53], v[18:21], v[34:37]
	v_exp_f32_e32 v40, v6
	v_sub_f32_e32 v6, v8, v125
	v_exp_f32_e32 v42, v6
	v_sub_f32_e32 v6, v9, v125
	v_sub_f32_e32 v0, 0xf149f2ca, v125
	v_exp_f32_e32 v66, v6
	v_sub_f32_e32 v6, v10, v125
	v_exp_f32_e32 v68, v6
	v_sub_f32_e32 v6, v11, v125
	v_exp_f32_e32 v146, v0
	v_maximum3_f32 v0, v14, v15, v16
	v_maximum3_f32 v10, v17, v34, v35
	v_maximum3_f32 v11, v36, v37, v37
	v_maximum3_f32 v0, v0, v10, v11
	v_mov_b32_e32 v10, v0
	s_nop 1
	v_permlane16_swap_b32_e32 v0, v10
	v_maximum3_f32 v0, v0, v10, v10
	v_mov_b32_e32 v10, v0
	s_nop 1
	v_permlane32_swap_b32_e32 v0, v10
	v_maximum3_f32 v124, v0, s0, v10
	v_exp_f32_e32 v98, v6
	v_sub_f32_e32 v6, v12, v125
	v_sub_f32_e32 v0, 0xf149f2ca, v124
	v_exp_f32_e32 v142, v6
	v_sub_f32_e32 v6, v13, v125
	v_sub_f32_e32 v10, v14, v124
	v_exp_f32_e32 v147, v0
	v_exp_f32_e32 v144, v6
	v_exp_f32_e32 v39, v10
	v_sub_f32_e32 v10, v15, v124
	v_exp_f32_e32 v41, v10
	v_sub_f32_e32 v10, v16, v124
	v_sub_f32_e32 v0, v34, v124
	v_exp_f32_e32 v43, v10
	v_sub_f32_e32 v10, v17, v124
	v_exp_f32_e32 v69, v0
	v_sub_f32_e32 v0, v35, v124
	v_exp_f32_e32 v67, v10
	v_pk_mul_f32 v[10:11], v[146:147], 0 op_sel_hi:[1,0]
	v_exp_f32_e32 v99, v0
	v_sub_f32_e32 v0, v36, v124
	v_cvt_pk_bf16_f32 v6, v38, v40
	v_cvt_pk_bf16_f32 v7, v42, v66
	v_cvt_pk_bf16_f32 v8, v68, v98
	v_cvt_pk_bf16_f32 v9, v142, v144
	v_mov_b32_e32 v14, v10
	v_mov_b32_e32 v15, v10
	v_mov_b32_e32 v16, v10
	v_mov_b32_e32 v17, v10
	v_exp_f32_e32 v143, v0
	v_sub_f32_e32 v0, v37, v124
	v_mfma_f32_16x16x32_bf16 v[54:57], v[70:73], v[6:9], v[14:17]
	v_exp_f32_e32 v145, v0
	v_mov_b32_e32 v10, v11
	v_mov_b32_e32 v12, v11
	s_waitcnt lgkmcnt(0)
	v_mfma_f32_16x16x32_bf16 v[62:65], v[74:77], v[6:9], v[14:17]
	v_mov_b32_e32 v13, v11
	v_cvt_pk_bf16_f32 v34, v39, v41
	v_cvt_pk_bf16_f32 v35, v43, v67
	v_mfma_f32_16x16x32_bf16 v[58:61], v[78:81], v[6:9], v[14:17]
	v_cvt_pk_bf16_f32 v36, v69, v99
	v_cvt_pk_bf16_f32 v37, v143, v145
	v_mfma_f32_16x16x32_bf16 v[50:53], v[126:129], v[6:9], v[14:17]
	v_add_f32_e64 v6, v38, 0
	v_add_f32_e64 v7, v39, 0
	v_pk_add_f32 v[6:7], v[40:41], v[6:7]
	v_mfma_f32_16x16x32_bf16 v[46:49], v[130:133], v[34:37], v[10:13]
	v_pk_add_f32 v[6:7], v[42:43], v[6:7]
	v_pk_add_f32 v[6:7], v[66:67], v[6:7]
	v_mfma_f32_16x16x32_bf16 v[42:45], v[134:137], v[34:37], v[10:13]
	v_pk_add_f32 v[6:7], v[68:69], v[6:7]
	v_pk_add_f32 v[6:7], v[98:99], v[6:7]
	v_mfma_f32_16x16x32_bf16 v[38:41], v[138:141], v[34:37], v[10:13]
	v_pk_add_f32 v[6:7], v[142:143], v[6:7]
	v_pk_add_f32 v[6:7], v[144:145], v[6:7]
	v_mfma_f32_16x16x32_bf16 v[34:37], v[2:5], v[34:37], v[10:13]
	v_fma_f32 v98, v146, 0, v6
	v_fma_f32 v99, v147, 0, v7
	s_cmp_eq_u32 s41, 1
	s_cbranch_scc1 .LBB0_281
	s_branch .LBB0_292

; #define GAS __attribute__((address_space(1)))
; #define DMA_TILE(t) do { const unsigned sl_ = (unsigned)__builtin_amdgcn_readfirstlane(ring0 + (unsigned)(((t) + base) % 3) * SLOT); \
;         glds16kv(loffk, loffv, kg + (size_t)(t) * 64 * PITCH, vg + (size_t)(t) * 64 * PITCH, sl_); } while (0)
; #define DMA_NEXT(i) do { const unsigned sl_ = (unsigned)__builtin_amdgcn_readfirstlane(ring0 + (unsigned)((nT + (i) + base) % 3) * SLOT); \
;         glds16kv(loffk, loffv, nK + (size_t)(i) * 64 * PITCH, nV + (size_t)(i) * 64 * PITCH, sl_); } while (0)
; template <int MODE> ...
;     ...
;         if (t >= 2) { if (t + 1 < nT || nK) asm volatile("s_waitcnt vmcnt(2)" ::: "memory"); else asm volatile("s_waitcnt vmcnt(0)" ::: "memory"); }
;         __builtin_amdgcn_s_barrier();
;         if (t + 2 < nT) DMA_TILE(t + 2); else if (nK) DMA_NEXT(t + 2 - nT);
;     ...
;     { const GAS bf16_t* qs = nQ ? (const GAS bf16_t*)nQ : (const GAS bf16_t*)proj + (size_t)qtok0 * NIN + qcol;
; #pragma unroll
;       for (int jj = 0; jj < 2; ++jj)
; #pragma unroll
;           for (int ks = 0; ks < 2; ++ks) qn[jj][ks] = *(const GAS bf16x8*)(qs + (size_t)(16 * jj) * NIN + 32 * ks + qoff); }
.LBB0_283:
	s_add_i32 s42, s86, s26
	s_add_i32 s0, s42, 1
	s_mul_hi_i32 s14, s0, 0x55555556
	s_lshr_b32 s15, s14, 31
	s_add_i32 s14, s14, s15
	s_mul_i32 s14, s14, 3
	s_sub_i32 s0, s0, s14
	s_lshl_b32 s0, s0, 14
	s_add_i32 s0, s0, s94
	s_add_u32 s34, s34, 0x48000
	s_addc_u32 s35, s35, 0
	s_add_u32 s30, s30, 0x48000
	s_barrier
	s_addc_u32 s31, s31, 0
	s_mov_b32 m0, s0
	s_nop 0
	global_load_lds_dwordx4 v84, s[34:35]
	s_add_u32 m0, m0, 0x2000
	s_nop 0
	global_load_lds_dwordx4 v85, s[30:31]
	v_lshl_add_u64 v[6:7], v[82:83], 1, s[38:39]
	global_load_dwordx4 v[2:5], v[6:7], off
	global_load_dwordx4 v[10:13], v[6:7], off offset:64
	v_add_co_u32_e32 v6, vcc, 0x12000, v6
	s_cmp_gt_u32 s40, s27
	s_nop 0
	v_addc_co_u32_e32 v7, vcc, 0, v7, vcc
	global_load_dwordx4 v[14:17], v[6:7], off
	s_nop 0
	global_load_dwordx4 v[6:9], v[6:7], off offset:64
	s_cselect_b64 s[30:31], -1, 0
	s_add_i32 s0, s23, 8
	s_cmp_le_i32 s26, s0
	s_cselect_b64 s[26:27], -1, 0
	s_and_b64 s[26:27], s[30:31], s[26:27]
	s_and_b64 vcc, exec, s[26:27]
	s_cbranch_vccz .LBB0_285
; #define LAS __attribute__((address_space(3)))
; template <int MODE> ...
;     ...
;                     for (int ks = 0; ks < 2; ++ks) kf[jj][kt][ks] = *(const LAS bf16x8*)(Sl + kad[jj][ks] + (32 * hf + 16 * kt) * 128);
;             f32x4 bb[2][2];
; #pragma unroll
;             for (int jj = 0; jj < 2; ++jj) { const LAS f32x4* bl = bcp + ((MODE == 0) ? (dr0 + t - act0) * 8 : 16 * t + 8 * hf) + bofs[jj];
; #pragma unroll
;                 for (int kt = 0; kt < 2; ++kt) bb[jj][kt] = bl[4 * kt]; }
;             s16x4 vlo[2][4], vhi[2][4];
; #pragma unroll
;             for (int jj = 0; jj < 2; ++jj)
; #pragma unroll
;                 for (int dt = 0; dt < 4; ++dt) { const LAS unsigned char* vp = Sl + vad[jj] + (32 * hf) * 128 + ((dt ^ sv) << 5);
;                     vlo[jj][dt] = __builtin_bit_cast(s16x4, __builtin_amdgcn_ds_read_tr16_b64_v4i16((LAS s16x4*)(vp)));
;                     vhi[jj][dt] = __builtin_bit_cast(s16x4, __builtin_amdgcn_ds_read_tr16_b64_v4i16((LAS s16x4*)(vp + 2048))); }
;             __builtin_amdgcn_sched_barrier(0);
;             f32x4 s[2][2];
; #pragma unroll
;             for (int jj = 0; jj < 2; ++jj)
; #pragma unroll
;                 for (int kt = 0; kt < 2; ++kt) { f32x4 a = (MODE == 0) ? bb[jj][kt] + mneg[jj][kt] : bb[jj][kt];
;                     a = __builtin_amdgcn_mfma_f32_16x16x32_bf16(kf[jj][kt][0], qf[jj][0], a, 0, 0, 0);
;                     s[jj][kt] = __builtin_amdgcn_mfma_f32_16x16x32_bf16(kf[jj][kt][1], qf[jj][1], a, 0, 0, 0); }
;             u32x4 pw[2];
; #pragma unroll
;             for (int jj = 0; jj < 2; ++jj) {
;                 const float tm = vmax3(vmax3(s[jj][0][0], s[jj][0][1], s[jj][0][2]), vmax3(s[jj][0][3], s[jj][1][0], s[jj][1][1]), vmax3(s[jj][1][2], s[jj][1][3], s[jj][1][3]));
;                 const float mn = quad_max3(mrun[jj], tm);
;                 const float alpha = __builtin_amdgcn_exp2f(mrun[jj] - mn);
;                 mrun[jj] = mn;
;                 float rsum = 0.f;
; #pragma unroll
;                 for (int kt = 0; kt < 2; ++kt)
; #pragma unroll
;                     for (int e = 0; e < 4; ++e) { s[jj][kt][e] = __builtin_amdgcn_exp2f(s[jj][kt][e] - mn); rsum += s[jj][kt][e]; }
;                 lrun[jj] = lrun[jj] * alpha + rsum;
; #pragma unroll
;                 for (int dt = 0; dt < 4; ++dt) o[jj][dt] *= alpha;
	s_add_i32 s0, s41, s86
	s_mul_hi_i32 s14, s0, 0x55555556
	s_lshr_b32 s15, s14, 31
	s_add_i32 s14, s14, s15
	s_mul_i32 s14, s14, 3
	s_sub_i32 s0, s0, s14
	s_lshl_b32 s0, s0, 14
	s_sub_i32 s14, s41, s23
	s_add_i32 s0, s0, 0
	s_add_i32 s14, s14, s25
	v_add_u32_e32 v0, s0, v89
	s_lshl_b32 s14, s14, 7
	v_add_u32_e32 v66, s0, v88
	ds_read_b128 v[126:129], v0
	ds_read_b128 v[130:133], v0 offset:2048
	ds_read_b128 v[134:137], v66
	ds_read_b128 v[138:141], v66 offset:2048
	v_add_u32_e32 v0, s0, v92
	s_add_i32 s24, s24, s14
	v_add_u32_e32 v66, s0, v91
	ds_read_b128 v[142:145], v0
	ds_read_b128 v[146:149], v0 offset:2048
	ds_read_b128 v[150:153], v66
	ds_read_b128 v[154:157], v66 offset:2048
	v_lshl_add_u32 v0, v87, 4, s24
	ds_read_b128 v[158:161], v0
	ds_read_b128 v[162:165], v0 offset:64
	v_lshl_add_u32 v0, v90, 4, s24
	ds_read_b128 v[166:169], v0
	ds_read_b128 v[170:173], v0 offset:64
	v_lshlrev_b32_e32 v0, 5, v93
	v_add3_u32 v66, v86, v122, s0
	v_add_u32_e32 v67, v66, v0
	v_xor_b32_e32 v68, 32, v0
	v_add_u32_e32 v69, v66, v68
	ds_read_b64_tr_b16 v[94:95], v67 offset:8192
	ds_read_b64_tr_b16 v[96:97], v67 offset:10240
	ds_read_b64_tr_b16 v[90:91], v69 offset:8192
	ds_read_b64_tr_b16 v[92:93], v69 offset:10240
	v_xor_b32_e32 v67, 64, v0
	v_xor_b32_e32 v70, 0x60, v0
	v_add_u32_e32 v69, v66, v67
	v_add_u32_e32 v66, v66, v70
	ds_read_b64_tr_b16 v[86:87], v69 offset:8192
	ds_read_b64_tr_b16 v[88:89], v69 offset:10240
	ds_read_b64_tr_b16 v[82:83], v66 offset:8192
	ds_read_b64_tr_b16 v[84:85], v66 offset:10240
	v_add3_u32 v66, v123, v122, s0
	v_add_u32_e32 v0, v66, v0
	v_add_u32_e32 v68, v66, v68
	ds_read_b64_tr_b16 v[78:79], v0 offset:8192
	ds_read_b64_tr_b16 v[80:81], v0 offset:10240
	ds_read_b64_tr_b16 v[74:75], v68 offset:8192
	ds_read_b64_tr_b16 v[76:77], v68 offset:10240
	v_add_u32_e32 v0, v66, v67
	v_add_u32_e32 v68, v66, v70
	ds_read_b64_tr_b16 v[70:71], v0 offset:8192
	ds_read_b64_tr_b16 v[72:73], v0 offset:10240
	ds_read_b64_tr_b16 v[66:67], v68 offset:8192
	ds_read_b64_tr_b16 v[68:69], v68 offset:10240
	s_waitcnt lgkmcnt(14)
	v_pk_add_f32 v[112:113], v[112:113], v[160:161]
	v_pk_add_f32 v[110:111], v[110:111], v[158:159]
	v_pk_add_f32 v[114:115], v[114:115], v[164:165]
	v_pk_add_f32 v[100:101], v[100:101], v[170:171]
	v_mfma_f32_16x16x32_bf16 v[110:113], v[126:129], v[30:33], v[110:113]
	v_mfma_f32_16x16x32_bf16 v[126:129], v[134:137], v[26:29], v[110:113]
	s_nop 6
	v_pk_add_f32 v[112:113], v[108:109], v[162:163]
	v_maximum3_f32 v0, v126, v127, v128
	v_pk_add_f32 v[108:109], v[106:107], v[168:169]
	v_mfma_f32_16x16x32_bf16 v[30:33], v[130:133], v[30:33], v[112:115]
	v_pk_add_f32 v[106:107], v[102:103], v[166:167]
	v_pk_add_f32 v[102:103], v[104:105], v[172:173]
	v_mfma_f32_16x16x32_bf16 v[26:29], v[138:141], v[26:29], v[30:33]
	s_nop 7
	v_maximum3_f32 v30, v129, v26, v27
	v_maximum3_f32 v31, v28, v29, v29
	v_maximum3_f32 v0, v0, v30, v31
	v_mov_b32_e32 v104, v0
	s_nop 1
	v_permlane16_swap_b32_e32 v0, v104
	v_mfma_f32_16x16x32_bf16 v[30:33], v[142:145], v[22:25], v[106:109]
	v_maximum3_f32 v0, v0, v104, v104
	v_mov_b32_e32 v104, v0
	s_nop 1
	v_permlane32_swap_b32_e32 v0, v104
	v_mfma_f32_16x16x32_bf16 v[22:25], v[146:149], v[22:25], v[100:103]
	v_maximum3_f32 v0, v125, v0, v104
	v_mfma_f32_16x16x32_bf16 v[30:33], v[150:153], v[18:21], v[30:33]
	s_nop 0
	v_sub_f32_e32 v100, v125, v0
	v_exp_f32_e32 v122, v100
	v_sub_f32_e32 v101, v126, v0
	v_mfma_f32_16x16x32_bf16 v[18:21], v[154:157], v[18:21], v[22:25]
	v_exp_f32_e32 v104, v101
	v_pk_mul_f32 v[60:61], v[60:61], v[122:123] op_sel_hi:[1,0]
	v_pk_mul_f32 v[58:59], v[58:59], v[122:123] op_sel_hi:[1,0]
	v_sub_f32_e32 v22, v127, v0
	v_exp_f32_e32 v106, v22
	v_sub_f32_e32 v22, v128, v0
	v_exp_f32_e32 v108, v22
	v_sub_f32_e32 v22, v129, v0
	v_exp_f32_e32 v110, v22
	v_sub_f32_e32 v22, v26, v0
	v_exp_f32_e32 v112, v22
	v_sub_f32_e32 v22, v27, v0
	v_exp_f32_e32 v114, v22
	v_sub_f32_e32 v22, v28, v0
	v_sub_f32_e32 v0, v29, v0
	v_exp_f32_e32 v126, v22
	v_exp_f32_e32 v128, v0
	v_pk_mul_f32 v[22:23], v[54:55], v[122:123] op_sel_hi:[1,0]
	v_maximum3_f32 v0, v30, v31, v32
	v_maximum3_f32 v54, v33, v18, v19
	v_maximum3_f32 v55, v20, v21, v21
	v_maximum3_f32 v0, v0, v54, v55
	v_mov_b32_e32 v54, v0
	s_nop 1
	v_permlane16_swap_b32_e32 v0, v54
	v_maximum3_f32 v0, v0, v54, v54
	v_mov_b32_e32 v54, v0
	s_nop 1
	v_permlane32_swap_b32_e32 v0, v54
	v_maximum3_f32 v0, v124, v0, v54
	v_sub_f32_e32 v30, v30, v0
	v_exp_f32_e32 v105, v30
	v_sub_f32_e32 v30, v31, v0
	v_exp_f32_e32 v107, v30
	v_sub_f32_e32 v30, v32, v0
	v_sub_f32_e32 v18, v18, v0
	v_exp_f32_e32 v109, v30
	v_sub_f32_e32 v30, v33, v0
	v_exp_f32_e32 v113, v18
	v_sub_f32_e32 v18, v19, v0
	v_sub_f32_e32 v54, v124, v0
	v_exp_f32_e32 v111, v30
	v_exp_f32_e32 v115, v18
	v_sub_f32_e32 v18, v20, v0
	v_pk_mul_f32 v[24:25], v[56:57], v[122:123] op_sel_hi:[1,0]
	v_pk_mul_f32 v[28:29], v[64:65], v[122:123] op_sel_hi:[1,0]
	v_pk_mul_f32 v[26:27], v[62:63], v[122:123] op_sel_hi:[1,0]
	v_pk_mul_f32 v[52:53], v[52:53], v[122:123] op_sel_hi:[1,0]
	v_pk_mul_f32 v[50:51], v[50:51], v[122:123] op_sel_hi:[1,0]
	v_exp_f32_e32 v127, v18
	v_sub_f32_e32 v0, v21, v0
	v_exp_f32_e32 v123, v54
	v_pk_add_f32 v[18:19], v[104:105], 0 op_sel_hi:[1,0]
	v_exp_f32_e32 v129, v0
	v_pk_add_f32 v[18:19], v[106:107], v[18:19]
	v_cvt_pk_bf16_f32 v100, v104, v106
	v_pk_add_f32 v[18:19], v[108:109], v[18:19]
	v_cvt_pk_bf16_f32 v101, v108, v110
	v_pk_add_f32 v[18:19], v[110:111], v[18:19]
	v_cvt_pk_bf16_f32 v102, v112, v114
	v_cvt_pk_bf16_f32 v103, v126, v128
	v_pk_add_f32 v[18:19], v[112:113], v[18:19]
	v_mov_b32_e32 v0, v123
	v_mfma_f32_16x16x32_bf16 v[54:57], v[94:97], v[100:103], v[22:25]
	v_pk_mul_f32 v[20:21], v[48:49], v[0:1] op_sel_hi:[1,0]
	s_waitcnt lgkmcnt(0)
	v_mfma_f32_16x16x32_bf16 v[62:65], v[90:93], v[100:103], v[26:29]
	v_cvt_pk_bf16_f32 v22, v105, v107
	v_cvt_pk_bf16_f32 v23, v109, v111
	v_cvt_pk_bf16_f32 v24, v113, v115
	v_pk_add_f32 v[26:27], v[114:115], v[18:19]
	v_pk_mul_f32 v[18:19], v[46:47], v[0:1] op_sel_hi:[1,0]
	v_cvt_pk_bf16_f32 v25, v127, v129
	v_mfma_f32_16x16x32_bf16 v[58:61], v[86:89], v[100:103], v[58:61]
	v_pk_add_f32 v[26:27], v[126:127], v[26:27]
	v_pk_add_f32 v[26:27], v[128:129], v[26:27]
	v_mfma_f32_16x16x32_bf16 v[46:49], v[78:81], v[22:25], v[18:21]
	v_fma_f32 v98, v98, v122, v26
	v_fma_f32 v99, v99, v123, v27
	s_nop 0
	v_pk_mul_f32 v[20:21], v[44:45], v[0:1] op_sel_hi:[1,0]
	v_pk_mul_f32 v[18:19], v[42:43], v[0:1] op_sel_hi:[1,0]
	v_mfma_f32_16x16x32_bf16 v[50:53], v[82:85], v[100:103], v[50:53]
	v_mfma_f32_16x16x32_bf16 v[42:45], v[74:77], v[22:25], v[18:21]
	s_nop 2
	v_pk_mul_f32 v[20:21], v[40:41], v[0:1] op_sel_hi:[1,0]
	v_pk_mul_f32 v[18:19], v[38:39], v[0:1] op_sel_hi:[1,0]
	s_nop 0
	v_mfma_f32_16x16x32_bf16 v[38:41], v[70:73], v[22:25], v[18:21]
	s_nop 2
	v_pk_mul_f32 v[20:21], v[36:37], v[0:1] op_sel_hi:[1,0]
	v_pk_mul_f32 v[18:19], v[34:35], v[0:1] op_sel_hi:[1,0]
	s_nop 0
	v_mfma_f32_16x16x32_bf16 v[34:37], v[66:69], v[22:25], v[18:21]

; template <int MODE> ...
;     ...
;         const LAS unsigned char* Sl = ring + ((t + base) % 3) * SLOT;
; #pragma unroll
;         for (int hf = 0; hf < NH; ++hf) {
;             if (MODE == 1) { const int ks = ktok0 + 64 * t + 32 * hf;
;                 if (ks + 31 < qtok0 - 128 || ks > qtok0 + 31 + 128) continue; }
;             bf16x8 kf[2][2][2];
; #pragma unroll
;             for (int jj = 0; jj < 2; ++jj)
; #pragma unroll
;                 for (int kt = 0; kt < 2; ++kt)
; #pragma unroll
;                     for (int ks = 0; ks < 2; ++ks) kf[jj][kt][ks] = *(const LAS bf16x8*)(Sl + kad[jj][ks] + (32 * hf + 16 * kt) * 128);
;             f32x4 bb[2][2];
; #pragma unroll
;             for (int jj = 0; jj < 2; ++jj) { const LAS f32x4* bl = bcp + ((MODE == 0) ? (dr0 + t - act0) * 8 : 16 * t + 8 * hf) + bofs[jj];
; #pragma unroll
;                 for (int kt = 0; kt < 2; ++kt) bb[jj][kt] = bl[4 * kt]; }
;             s16x4 vlo[2][4], vhi[2][4];
; #pragma unroll
;             for (int jj = 0; jj < 2; ++jj)
; #pragma unroll
;                 for (int dt = 0; dt < 4; ++dt) { const LAS unsigned char* vp = Sl + vad[jj] + (32 * hf) * 128 + ((dt ^ sv) << 5);
;                     vlo[jj][dt] = __builtin_bit_cast(s16x4, __builtin_amdgcn_ds_read_tr16_b64_v4i16((LAS s16x4*)(vp)));
;                     vhi[jj][dt] = __builtin_bit_cast(s16x4, __builtin_amdgcn_ds_read_tr16_b64_v4i16((LAS s16x4*)(vp + 2048))); }
;             __builtin_amdgcn_sched_barrier(0);
;             f32x4 s[2][2];
; #pragma unroll
;             for (int jj = 0; jj < 2; ++jj)
; #pragma unroll
;                 for (int kt = 0; kt < 2; ++kt) { f32x4 a = (MODE == 0) ? bb[jj][kt] + mneg[jj][kt] : bb[jj][kt];
;                     a = __builtin_amdgcn_mfma_f32_16x16x32_bf16(kf[jj][kt][0], qf[jj][0], a, 0, 0, 0);
;                     s[jj][kt] = __builtin_amdgcn_mfma_f32_16x16x32_bf16(kf[jj][kt][1], qf[jj][1], a, 0, 0, 0); }
;             u32x4 pw[2];
; #pragma unroll
;             for (int jj = 0; jj < 2; ++jj) {
;                 const float tm = vmax3(vmax3(s[jj][0][0], s[jj][0][1], s[jj][0][2]), vmax3(s[jj][0][3], s[jj][1][0], s[jj][1][1]), vmax3(s[jj][1][2], s[jj][1][3], s[jj][1][3]));
;                 const float mn = quad_max3(mrun[jj], tm);
;                 const float alpha = __builtin_amdgcn_exp2f(mrun[jj] - mn);
;                 mrun[jj] = mn;
;                 float rsum = 0.f;
.LBB0_298:
	s_add_i32 s0, s86, 1
	s_mul_hi_i32 s14, s0, 0x55555556
	s_lshr_b32 s15, s14, 31
	s_add_i32 s14, s14, s15
	s_mul_i32 s14, s14, 3
	s_sub_i32 s0, s0, s14
	s_lshl_b32 s0, s0, 14
	s_add_i32 s0, s0, 0
	v_add_u32_e32 v0, s0, v89
	s_lshl_b32 s14, s52, 7
	v_add_u32_e32 v2, s0, v88
	ds_read_b128 v[126:129], v0
	ds_read_b128 v[130:133], v0 offset:2048
	ds_read_b128 v[134:137], v2
	ds_read_b128 v[138:141], v2 offset:2048
	v_add_u32_e32 v0, s0, v92
	s_add_i32 s14, s24, s14
	v_add_u32_e32 v2, s0, v91
	ds_read_b128 v[142:145], v0
	ds_read_b128 v[146:149], v0 offset:2048
	ds_read_b128 v[150:153], v2
	ds_read_b128 v[154:157], v2 offset:2048
	v_lshl_add_u32 v0, v87, 4, s14
	ds_read_b128 v[158:161], v0 offset:128
	ds_read_b128 v[162:165], v0 offset:192
	v_lshl_add_u32 v0, v90, 4, s14
	ds_read_b128 v[166:169], v0 offset:128
	ds_read_b128 v[170:173], v0 offset:192
	v_add3_u32 v0, v86, v122, s0
	v_add_u32_e32 v2, v0, v94
	v_add_u32_e32 v3, v0, v95
	ds_read_b64_tr_b16 v[78:79], v2 offset:8192
	ds_read_b64_tr_b16 v[80:81], v2 offset:10240
	ds_read_b64_tr_b16 v[74:75], v3 offset:8192
	ds_read_b64_tr_b16 v[76:77], v3 offset:10240
	v_add_u32_e32 v2, v0, v96
	v_add_u32_e32 v0, v0, v97
	ds_read_b64_tr_b16 v[70:71], v2 offset:8192
	ds_read_b64_tr_b16 v[72:73], v2 offset:10240
	ds_read_b64_tr_b16 v[66:67], v0 offset:8192
	ds_read_b64_tr_b16 v[68:69], v0 offset:10240
	v_add3_u32 v0, v123, v122, s0
	v_add_u32_e32 v2, v0, v94
	v_add_u32_e32 v3, v0, v95
	ds_read_b64_tr_b16 v[14:15], v2 offset:8192
	ds_read_b64_tr_b16 v[16:17], v2 offset:10240
	ds_read_b64_tr_b16 v[10:11], v3 offset:8192
	ds_read_b64_tr_b16 v[12:13], v3 offset:10240
	v_add_u32_e32 v2, v0, v96
	v_add_u32_e32 v0, v0, v97
	ds_read_b64_tr_b16 v[6:7], v2 offset:8192
	ds_read_b64_tr_b16 v[8:9], v2 offset:10240
	ds_read_b64_tr_b16 v[2:3], v0 offset:8192
	ds_read_b64_tr_b16 v[4:5], v0 offset:10240
	s_waitcnt lgkmcnt(14)
	v_pk_add_f32 v[160:161], v[112:113], v[160:161]
	v_pk_add_f32 v[158:159], v[110:111], v[158:159]
	s_nop 1
	v_mfma_f32_16x16x32_bf16 v[126:129], v[126:129], v[30:33], v[158:161]
	s_nop 2
	v_pk_add_f32 v[160:161], v[114:115], v[164:165]
	v_pk_add_f32 v[158:159], v[108:109], v[162:163]
	v_mfma_f32_16x16x32_bf16 v[126:129], v[134:137], v[26:29], v[126:129]
	v_pk_add_f32 v[136:137], v[106:107], v[168:169]
	v_pk_add_f32 v[134:135], v[102:103], v[166:167]
	v_mfma_f32_16x16x32_bf16 v[130:133], v[130:133], v[30:33], v[158:161]
	v_mfma_f32_16x16x32_bf16 v[130:133], v[138:141], v[26:29], v[130:133]
	s_nop 2
	v_maximum3_f32 v0, v126, v127, v128
	v_pk_add_f32 v[160:161], v[104:105], v[172:173]
	v_pk_add_f32 v[158:159], v[100:101], v[170:171]
	v_mfma_f32_16x16x32_bf16 v[134:137], v[142:145], v[22:25], v[134:137]
	v_mfma_f32_16x16x32_bf16 v[134:137], v[150:153], v[18:21], v[134:137]
	v_maximum3_f32 v138, v129, v130, v131
	v_maximum3_f32 v139, v132, v133, v133
	v_maximum3_f32 v0, v0, v138, v139
	v_mov_b32_e32 v138, v0
	s_nop 1
	v_permlane16_swap_b32_e32 v0, v138
	v_maximum3_f32 v0, v0, v138, v138
	v_mov_b32_e32 v138, v0
	s_nop 1
	v_permlane32_swap_b32_e32 v0, v138
	v_maximum3_f32 v162, v125, v0, v138
	v_mfma_f32_16x16x32_bf16 v[138:141], v[146:149], v[22:25], v[158:161]
	v_sub_f32_e32 v0, v125, v162
	v_sub_f32_e32 v125, v126, v162
	v_exp_f32_e32 v142, v125
	v_sub_f32_e32 v125, v127, v162
	v_exp_f32_e32 v144, v125
	v_sub_f32_e32 v125, v128, v162
	v_mfma_f32_16x16x32_bf16 v[138:141], v[154:157], v[18:21], v[138:141]
	v_exp_f32_e32 v146, v125
	v_sub_f32_e32 v125, v129, v162
	v_exp_f32_e32 v148, v125
	v_sub_f32_e32 v125, v130, v162
	v_exp_f32_e32 v130, v125
	v_sub_f32_e32 v125, v131, v162
	v_exp_f32_e32 v150, v125
	v_sub_f32_e32 v125, v132, v162
	v_exp_f32_e32 v132, v0
	v_sub_f32_e32 v0, v133, v162
	v_exp_f32_e32 v152, v125
	v_exp_f32_e32 v154, v0
	v_maximum3_f32 v0, v134, v135, v136
	v_maximum3_f32 v125, v137, v138, v139
	v_maximum3_f32 v129, v140, v141, v141
	v_maximum3_f32 v0, v0, v125, v129
	v_mov_b32_e32 v125, v0
	s_nop 1
	v_permlane16_swap_b32_e32 v0, v125
	v_maximum3_f32 v0, v0, v125, v125
	v_mov_b32_e32 v125, v0
	s_nop 1
	v_permlane32_swap_b32_e32 v0, v125
	v_maximum3_f32 v156, v124, v0, v125
	v_pk_mul_f32 v[56:57], v[56:57], v[132:133] op_sel_hi:[1,0]
	v_pk_mul_f32 v[54:55], v[54:55], v[132:133] op_sel_hi:[1,0]
	v_pk_mul_f32 v[64:65], v[64:65], v[132:133] op_sel_hi:[1,0]
	v_pk_mul_f32 v[62:63], v[62:63], v[132:133] op_sel_hi:[1,0]
	v_pk_mul_f32 v[60:61], v[60:61], v[132:133] op_sel_hi:[1,0]
	v_pk_mul_f32 v[58:59], v[58:59], v[132:133] op_sel_hi:[1,0]
	v_pk_mul_f32 v[52:53], v[52:53], v[132:133] op_sel_hi:[1,0]
	v_pk_mul_f32 v[50:51], v[50:51], v[132:133] op_sel_hi:[1,0]
	v_sub_f32_e32 v0, v134, v156
	v_sub_f32_e32 v133, v139, v156
	v_exp_f32_e32 v143, v0
	v_sub_f32_e32 v0, v135, v156
	v_sub_f32_e32 v131, v136, v156
	v_exp_f32_e32 v151, v133
	v_sub_f32_e32 v133, v140, v156
	v_exp_f32_e32 v145, v0
	v_sub_f32_e32 v0, v124, v156
	v_exp_f32_e32 v147, v131
	v_sub_f32_e32 v131, v137, v156
	v_exp_f32_e32 v153, v133
	v_sub_f32_e32 v133, v141, v156
	v_exp_f32_e32 v149, v131
	v_sub_f32_e32 v131, v138, v156
	v_exp_f32_e32 v155, v133
	v_exp_f32_e32 v133, v0
	v_exp_f32_e32 v131, v131
	v_cvt_pk_bf16_f32 v126, v142, v144
	v_cvt_pk_bf16_f32 v127, v146, v148
	v_cvt_pk_bf16_f32 v128, v130, v150
	v_cvt_pk_bf16_f32 v129, v152, v154
	v_pk_add_f32 v[124:125], v[142:143], 0 op_sel_hi:[1,0]
	v_mov_b32_e32 v0, v133
	v_pk_add_f32 v[124:125], v[144:145], v[124:125]
	s_waitcnt lgkmcnt(0)
	v_mfma_f32_16x16x32_bf16 v[58:61], v[70:73], v[126:129], v[58:61]
	v_pk_mul_f32 v[48:49], v[48:49], v[0:1] op_sel_hi:[1,0]
	v_pk_mul_f32 v[46:47], v[46:47], v[0:1] op_sel_hi:[1,0]
	v_cvt_pk_bf16_f32 v70, v143, v145
	v_cvt_pk_bf16_f32 v71, v147, v149
	v_cvt_pk_bf16_f32 v72, v131, v151
	v_cvt_pk_bf16_f32 v73, v153, v155
	v_mfma_f32_16x16x32_bf16 v[54:57], v[78:81], v[126:129], v[54:57]
	v_pk_add_f32 v[78:79], v[146:147], v[124:125]
	v_pk_add_f32 v[78:79], v[148:149], v[78:79]
	v_mfma_f32_16x16x32_bf16 v[46:49], v[14:17], v[70:73], v[46:49]
	v_pk_mul_f32 v[16:17], v[44:45], v[0:1] op_sel_hi:[1,0]
	v_pk_mul_f32 v[14:15], v[42:43], v[0:1] op_sel_hi:[1,0]
	v_mfma_f32_16x16x32_bf16 v[62:65], v[74:77], v[126:129], v[62:65]
	v_pk_add_f32 v[74:75], v[130:131], v[78:79]
	v_pk_add_f32 v[74:75], v[150:151], v[74:75]
	v_mfma_f32_16x16x32_bf16 v[42:45], v[10:13], v[70:73], v[14:17]
	v_pk_mul_f32 v[12:13], v[40:41], v[0:1] op_sel_hi:[1,0]
	v_pk_mul_f32 v[10:11], v[38:39], v[0:1] op_sel_hi:[1,0]
	v_mfma_f32_16x16x32_bf16 v[50:53], v[66:69], v[126:129], v[50:53]
	v_pk_add_f32 v[66:67], v[152:153], v[74:75]
	v_pk_add_f32 v[14:15], v[154:155], v[66:67]
	v_mfma_f32_16x16x32_bf16 v[38:41], v[6:9], v[70:73], v[10:13]
	v_pk_mul_f32 v[8:9], v[36:37], v[0:1] op_sel_hi:[1,0]
	v_pk_mul_f32 v[6:7], v[34:35], v[0:1] op_sel_hi:[1,0]
	v_pk_fma_f32 v[98:99], v[98:99], v[132:133], v[14:15]
	v_mfma_f32_16x16x32_bf16 v[34:37], v[2:5], v[70:73], v[6:9]
	v_mov_b32_e32 v125, v162
	v_mov_b32_e32 v124, v156
	s_cmp_eq_u32 s41, 2
	s_cbranch_scc1 .LBB0_281

; #define LAS __attribute__((address_space(3)))
; template <int MODE> ...
;     ...
;         if (t >= act0 && t < act0 + actn) {
;         const LAS unsigned char* Sl = ring + ((t + base) % 3) * SLOT;
; #pragma unroll
;         for (int hf = 0; hf < NH; ++hf) {
;             if (MODE == 1) { const int ks = ktok0 + 64 * t + 32 * hf;
;                 if (ks + 31 < qtok0 - 128 || ks > qtok0 + 31 + 128) continue; }
;             bf16x8 kf[2][2][2];
; #pragma unroll
;             for (int jj = 0; jj < 2; ++jj)
; #pragma unroll
;                 for (int kt = 0; kt < 2; ++kt)
; #pragma unroll
;                     for (int ks = 0; ks < 2; ++ks) kf[jj][kt][ks] = *(const LAS bf16x8*)(Sl + kad[jj][ks] + (32 * hf + 16 * kt) * 128);
;             f32x4 bb[2][2];
; #pragma unroll
;             for (int jj = 0; jj < 2; ++jj) { const LAS f32x4* bl = bcp + ((MODE == 0) ? (dr0 + t - act0) * 8 : 16 * t + 8 * hf) + bofs[jj];
; #pragma unroll
;                 for (int kt = 0; kt < 2; ++kt) bb[jj][kt] = bl[4 * kt]; }
;             s16x4 vlo[2][4], vhi[2][4];
; #pragma unroll
;             for (int jj = 0; jj < 2; ++jj)
; #pragma unroll
;                 for (int dt = 0; dt < 4; ++dt) { const LAS unsigned char* vp = Sl + vad[jj] + (32 * hf) * 128 + ((dt ^ sv) << 5);
;                     vlo[jj][dt] = __builtin_bit_cast(s16x4, __builtin_amdgcn_ds_read_tr16_b64_v4i16((LAS s16x4*)(vp)));
;                     vhi[jj][dt] = __builtin_bit_cast(s16x4, __builtin_amdgcn_ds_read_tr16_b64_v4i16((LAS s16x4*)(vp + 2048))); }
;             __builtin_amdgcn_sched_barrier(0);
.LBB0_305:
	s_add_i32 s0, s65, 2
	s_cmp_ge_i32 s0, s23
	s_cselect_b64 s[60:61], -1, 0
	s_cmp_lt_i32 s0, s45
	s_cselect_b64 s[66:67], -1, 0
	s_and_b64 s[60:61], s[60:61], s[66:67]
	s_andn2_b64 vcc, exec, s[60:61]
	s_cbranch_vccnz .LBB0_300
	s_add_i32 s0, s86, s65
	s_add_i32 s0, s0, 2
	s_mul_hi_i32 s14, s0, 0x55555556
	s_lshr_b32 s15, s14, 31
	s_add_i32 s14, s14, s15
	s_mul_i32 s14, s14, 3
	s_sub_i32 s0, s0, s14
	s_lshl_b32 s0, s0, 14
	s_add_i32 s0, s0, 0
	v_add_u32_e32 v2, s0, v89
	v_add_u32_e32 v3, s0, v88
	ds_read_b128 v[130:133], v2
	ds_read_b128 v[134:137], v2 offset:2048
	ds_read_b128 v[138:141], v3
	ds_read_b128 v[142:145], v3 offset:2048
	v_add_u32_e32 v2, s0, v92
	v_add_u32_e32 v3, s0, v91
	ds_read_b128 v[146:149], v2
	ds_read_b128 v[150:153], v2 offset:2048
	ds_read_b128 v[154:157], v3
	ds_read_b128 v[158:161], v3 offset:2048
	v_add_u32_e32 v2, s50, v128
	v_add_u32_e32 v3, s50, v127
	ds_read_b128 v[162:165], v2
	ds_read_b128 v[166:169], v2 offset:64
	ds_read_b128 v[170:173], v3
	ds_read_b128 v[174:177], v3 offset:64
	v_add_u32_e32 v3, s0, v178
	v_add_u32_e32 v4, s0, v179
	ds_read_b64_tr_b16 v[78:79], v3 offset:8192
	ds_read_b64_tr_b16 v[80:81], v3 offset:10240
	ds_read_b64_tr_b16 v[74:75], v4 offset:8192
	ds_read_b64_tr_b16 v[76:77], v4 offset:10240
	v_add_u32_e32 v3, s0, v180
	v_add_u32_e32 v2, s0, v181
	ds_read_b64_tr_b16 v[70:71], v3 offset:8192
	ds_read_b64_tr_b16 v[72:73], v3 offset:10240
	ds_read_b64_tr_b16 v[66:67], v2 offset:8192
	ds_read_b64_tr_b16 v[68:69], v2 offset:10240
	v_add_u32_e32 v3, s0, v182
	v_add_u32_e32 v4, s0, v183
	ds_read_b64_tr_b16 v[14:15], v3 offset:8192
	ds_read_b64_tr_b16 v[16:17], v3 offset:10240
	ds_read_b64_tr_b16 v[10:11], v4 offset:8192
	ds_read_b64_tr_b16 v[12:13], v4 offset:10240
	v_add_u32_e32 v3, s0, v184
	v_add_u32_e32 v4, s0, v185
	ds_read_b64_tr_b16 v[6:7], v3 offset:8192
	ds_read_b64_tr_b16 v[8:9], v3 offset:10240
	ds_read_b64_tr_b16 v[2:3], v4 offset:8192
	ds_read_b64_tr_b16 v[4:5], v4 offset:10240
	s_waitcnt lgkmcnt(14)
; __device__ __forceinline__ unsigned cvtpk(float lo, float hi) { f32x2 v = {lo, hi}; bf16x2_t b = __builtin_convertvector(v, bf16x2_t); return __builtin_bit_cast(unsigned, b); }
; __device__ __forceinline__ float vmax3(float a, float b, float c) { return __builtin_elementwise_maximum(__builtin_elementwise_maximum(a, b), c); }
; template <int MODE> ...
;     ...
;             f32x4 s[2][2];
; #pragma unroll
;             for (int jj = 0; jj < 2; ++jj)
; #pragma unroll
;                 for (int kt = 0; kt < 2; ++kt) { f32x4 a = (MODE == 0) ? bb[jj][kt] + mneg[jj][kt] : bb[jj][kt];
;                     a = __builtin_amdgcn_mfma_f32_16x16x32_bf16(kf[jj][kt][0], qf[jj][0], a, 0, 0, 0);
;                     s[jj][kt] = __builtin_amdgcn_mfma_f32_16x16x32_bf16(kf[jj][kt][1], qf[jj][1], a, 0, 0, 0); }
;             u32x4 pw[2];
; #pragma unroll
;             for (int jj = 0; jj < 2; ++jj) {
;                 const float tm = vmax3(vmax3(s[jj][0][0], s[jj][0][1], s[jj][0][2]), vmax3(s[jj][0][3], s[jj][1][0], s[jj][1][1]), vmax3(s[jj][1][2], s[jj][1][3], s[jj][1][3]));
;                 const float mn = quad_max3(mrun[jj], tm);
;                 const float alpha = __builtin_amdgcn_exp2f(mrun[jj] - mn);
;                 mrun[jj] = mn;
;                 float rsum = 0.f;
; #pragma unroll
;                 for (int kt = 0; kt < 2; ++kt)
; #pragma unroll
;                     for (int e = 0; e < 4; ++e) { s[jj][kt][e] = __builtin_amdgcn_exp2f(s[jj][kt][e] - mn); rsum += s[jj][kt][e]; }
;                 lrun[jj] = lrun[jj] * alpha + rsum;
; #pragma unroll
;                 for (int dt = 0; dt < 4; ++dt) o[jj][dt] *= alpha;
;                 pw[jj].x = cvtpk(s[jj][0][0], s[jj][0][1]); pw[jj].y = cvtpk(s[jj][0][2], s[jj][0][3]); pw[jj].z = cvtpk(s[jj][1][0], s[jj][1][1]); pw[jj].w = cvtpk(s[jj][1][2], s[jj][1][3]);
;             }
; #pragma unroll
;             for (int jj = 0; jj < 2; ++jj)
; #pragma unroll
;                 for (int dt = 0; dt < 4; ++dt) {
;                     const bf16x8 vf = (bf16x8){vlo[jj][dt][0], vlo[jj][dt][1], vlo[jj][dt][2], vlo[jj][dt][3], vhi[jj][dt][0], vhi[jj][dt][1], vhi[jj][dt][2], vhi[jj][dt][3]};
;                     o[jj][dt] = __builtin_amdgcn_mfma_f32_16x16x32_bf16(vf, __builtin_bit_cast(bf16x8, pw[jj]), o[jj][dt], 0, 0, 0); }
;             __builtin_amdgcn_sched_barrier(0);
	v_pk_add_f32 v[164:165], v[112:113], v[164:165]
	v_pk_add_f32 v[162:163], v[110:111], v[162:163]
	s_nop 1
	v_mfma_f32_16x16x32_bf16 v[130:133], v[130:133], v[30:33], v[162:165]
	s_nop 2
	v_pk_add_f32 v[164:165], v[114:115], v[168:169]
	v_pk_add_f32 v[162:163], v[108:109], v[166:167]
	v_mfma_f32_16x16x32_bf16 v[130:133], v[138:141], v[26:29], v[130:133]
	v_pk_add_f32 v[140:141], v[106:107], v[172:173]
	v_pk_add_f32 v[138:139], v[102:103], v[170:171]
	v_mfma_f32_16x16x32_bf16 v[134:137], v[134:137], v[30:33], v[162:165]
	v_mfma_f32_16x16x32_bf16 v[134:137], v[142:145], v[26:29], v[134:137]
	s_nop 2
	v_maximum3_f32 v129, v130, v131, v132
	v_pk_add_f32 v[164:165], v[104:105], v[176:177]
	v_pk_add_f32 v[162:163], v[100:101], v[174:175]
	v_mfma_f32_16x16x32_bf16 v[138:141], v[146:149], v[22:25], v[138:141]
	v_mfma_f32_16x16x32_bf16 v[138:141], v[154:157], v[18:21], v[138:141]
	v_maximum3_f32 v142, v133, v134, v135
	v_maximum3_f32 v143, v136, v137, v137
	v_maximum3_f32 v129, v129, v142, v143
	v_mov_b32_e32 v142, v129
	s_nop 1
	v_permlane16_swap_b32_e32 v129, v142
	v_maximum3_f32 v129, v129, v142, v142
	v_mov_b32_e32 v142, v129
	s_nop 1
	v_permlane32_swap_b32_e32 v129, v142
	v_maximum3_f32 v129, v125, v129, v142
	v_mfma_f32_16x16x32_bf16 v[142:145], v[150:153], v[22:25], v[162:165]
	v_pk_add_f32 v[130:131], v[130:131], v[128:129] op_sel:[0,1] op_sel_hi:[1,1] neg_lo:[0,1] neg_hi:[0,1]
	v_pk_add_f32 v[132:133], v[132:133], v[128:129] op_sel:[0,1] op_sel_hi:[1,1] neg_lo:[0,1] neg_hi:[0,1]
	v_pk_add_f32 v[134:135], v[134:135], v[128:129] op_sel:[0,1] op_sel_hi:[1,1] neg_lo:[0,1] neg_hi:[0,1]
	v_pk_add_f32 v[136:137], v[136:137], v[128:129] op_sel:[0,1] op_sel_hi:[1,1] neg_lo:[0,1] neg_hi:[0,1]
	v_sub_f32_e32 v125, v125, v129
	v_mfma_f32_16x16x32_bf16 v[142:145], v[158:161], v[18:21], v[142:145]
	v_exp_f32_e32 v146, v130
	v_exp_f32_e32 v148, v131
	v_exp_f32_e32 v150, v132
	v_exp_f32_e32 v152, v133
	v_exp_f32_e32 v154, v135
	v_exp_f32_e32 v156, v136
	v_exp_f32_e32 v158, v137
	v_exp_f32_e32 v134, v134
	v_exp_f32_e32 v136, v125
	v_maximum3_f32 v125, v138, v139, v140
	v_maximum3_f32 v133, v141, v142, v143
	v_maximum3_f32 v135, v144, v145, v145
	v_maximum3_f32 v125, v125, v133, v135
	v_mov_b32_e32 v133, v125
	s_nop 1
	v_permlane16_swap_b32_e32 v125, v133
	v_maximum3_f32 v125, v125, v133, v133
	v_mov_b32_e32 v133, v125
	s_nop 1
	v_permlane32_swap_b32_e32 v125, v133
	v_maximum3_f32 v160, v124, v125, v133
	v_pk_add_f32 v[138:139], v[138:139], v[160:161] op_sel_hi:[1,0] neg_lo:[0,1] neg_hi:[0,1]
	v_pk_add_f32 v[140:141], v[140:141], v[160:161] op_sel_hi:[1,0] neg_lo:[0,1] neg_hi:[0,1]
	v_pk_add_f32 v[142:143], v[142:143], v[160:161] op_sel_hi:[1,0] neg_lo:[0,1] neg_hi:[0,1]
	v_pk_add_f32 v[144:145], v[144:145], v[160:161] op_sel_hi:[1,0] neg_lo:[0,1] neg_hi:[0,1]
	v_sub_f32_e32 v137, v124, v160
	v_exp_f32_e32 v147, v138
	v_pk_mul_f32 v[56:57], v[56:57], v[136:137] op_sel_hi:[1,0]
	v_exp_f32_e32 v149, v139
	v_pk_mul_f32 v[54:55], v[54:55], v[136:137] op_sel_hi:[1,0]
	v_exp_f32_e32 v151, v140
	v_pk_mul_f32 v[64:65], v[64:65], v[136:137] op_sel_hi:[1,0]
	v_exp_f32_e32 v153, v141
	v_pk_mul_f32 v[62:63], v[62:63], v[136:137] op_sel_hi:[1,0]
	v_exp_f32_e32 v155, v143
	v_pk_mul_f32 v[60:61], v[60:61], v[136:137] op_sel_hi:[1,0]
	v_exp_f32_e32 v157, v144
	v_pk_mul_f32 v[58:59], v[58:59], v[136:137] op_sel_hi:[1,0]
	v_exp_f32_e32 v159, v145
	v_pk_mul_f32 v[52:53], v[52:53], v[136:137] op_sel_hi:[1,0]
	v_exp_f32_e32 v135, v142
	v_pk_mul_f32 v[50:51], v[50:51], v[136:137] op_sel_hi:[1,0]
	v_exp_f32_e32 v137, v137
	v_cvt_pk_bf16_f32 v130, v146, v148
	v_cvt_pk_bf16_f32 v131, v150, v152
	v_cvt_pk_bf16_f32 v132, v134, v154
	v_cvt_pk_bf16_f32 v133, v156, v158
	s_waitcnt lgkmcnt(0)
	v_mfma_f32_16x16x32_bf16 v[62:65], v[74:77], v[130:133], v[62:65]
	v_pk_add_f32 v[124:125], v[146:147], v[148:149]
	v_pk_mul_f32 v[48:49], v[48:49], v[136:137] op_sel:[0,1] op_sel_hi:[1,1]
	v_mfma_f32_16x16x32_bf16 v[58:61], v[70:73], v[130:133], v[58:61]
	v_pk_mul_f32 v[46:47], v[46:47], v[136:137] op_sel:[0,1] op_sel_hi:[1,1]
	v_cvt_pk_bf16_f32 v70, v147, v149
	v_cvt_pk_bf16_f32 v71, v151, v153
	v_cvt_pk_bf16_f32 v72, v135, v155
	v_cvt_pk_bf16_f32 v73, v157, v159
	v_mfma_f32_16x16x32_bf16 v[54:57], v[78:81], v[130:133], v[54:57]
	v_pk_add_f32 v[78:79], v[150:151], v[124:125]
	v_pk_add_f32 v[78:79], v[152:153], v[78:79]
	v_mfma_f32_16x16x32_bf16 v[46:49], v[14:17], v[70:73], v[46:49]
	v_pk_mul_f32 v[16:17], v[44:45], v[136:137] op_sel:[0,1] op_sel_hi:[1,1]
	v_pk_mul_f32 v[14:15], v[42:43], v[136:137] op_sel:[0,1] op_sel_hi:[1,1]
	v_pk_add_f32 v[74:75], v[134:135], v[78:79]
	v_mfma_f32_16x16x32_bf16 v[50:53], v[66:69], v[130:133], v[50:53]
	v_pk_add_f32 v[74:75], v[154:155], v[74:75]
	v_pk_add_f32 v[66:67], v[156:157], v[74:75]
	v_mfma_f32_16x16x32_bf16 v[42:45], v[10:13], v[70:73], v[14:17]
	v_pk_mul_f32 v[12:13], v[40:41], v[136:137] op_sel:[0,1] op_sel_hi:[1,1]
	v_pk_mul_f32 v[10:11], v[38:39], v[136:137] op_sel:[0,1] op_sel_hi:[1,1]
	v_pk_add_f32 v[14:15], v[158:159], v[66:67]
	v_mfma_f32_16x16x32_bf16 v[38:41], v[6:9], v[70:73], v[10:13]
	v_pk_mul_f32 v[8:9], v[36:37], v[136:137] op_sel:[0,1] op_sel_hi:[1,1]
	v_pk_mul_f32 v[6:7], v[34:35], v[136:137] op_sel:[0,1] op_sel_hi:[1,1]
	v_pk_fma_f32 v[98:99], v[98:99], v[136:137], v[14:15]
	v_mfma_f32_16x16x32_bf16 v[34:37], v[2:5], v[70:73], v[6:9]
	v_mov_b32_e32 v125, v129
	v_mov_b32_e32 v124, v160
	s_branch .LBB0_300

; template <int MODE> ...
;     ...
;         const LAS unsigned char* Sl = ring + ((t + base) % 3) * SLOT;
; #pragma unroll
;         for (int hf = 0; hf < NH; ++hf) {
;             if (MODE == 1) { const int ks = ktok0 + 64 * t + 32 * hf;
;                 if (ks + 31 < qtok0 - 128 || ks > qtok0 + 31 + 128) continue; }
;             bf16x8 kf[2][2][2];
; #pragma unroll
;             for (int jj = 0; jj < 2; ++jj)
; #pragma unroll
;                 for (int kt = 0; kt < 2; ++kt)
; #pragma unroll
;                     for (int ks = 0; ks < 2; ++ks) kf[jj][kt][ks] = *(const LAS bf16x8*)(Sl + kad[jj][ks] + (32 * hf + 16 * kt) * 128);
;             f32x4 bb[2][2];
; #pragma unroll
;             for (int jj = 0; jj < 2; ++jj) { const LAS f32x4* bl = bcp + ((MODE == 0) ? (dr0 + t - act0) * 8 : 16 * t + 8 * hf) + bofs[jj];
; #pragma unroll
;                 for (int kt = 0; kt < 2; ++kt) bb[jj][kt] = bl[4 * kt]; }
;             s16x4 vlo[2][4], vhi[2][4];
; #pragma unroll
;             for (int jj = 0; jj < 2; ++jj)
; #pragma unroll
;                 for (int dt = 0; dt < 4; ++dt) { const LAS unsigned char* vp = Sl + vad[jj] + (32 * hf) * 128 + ((dt ^ sv) << 5);
;                     vlo[jj][dt] = __builtin_bit_cast(s16x4, __builtin_amdgcn_ds_read_tr16_b64_v4i16((LAS s16x4*)(vp)));
;                     vhi[jj][dt] = __builtin_bit_cast(s16x4, __builtin_amdgcn_ds_read_tr16_b64_v4i16((LAS s16x4*)(vp + 2048))); }
;             __builtin_amdgcn_sched_barrier(0);
;             f32x4 s[2][2];
; #pragma unroll
;             for (int jj = 0; jj < 2; ++jj)
; #pragma unroll
;                 for (int kt = 0; kt < 2; ++kt) { f32x4 a = (MODE == 0) ? bb[jj][kt] + mneg[jj][kt] : bb[jj][kt];
;                     a = __builtin_amdgcn_mfma_f32_16x16x32_bf16(kf[jj][kt][0], qf[jj][0], a, 0, 0, 0);
;                     s[jj][kt] = __builtin_amdgcn_mfma_f32_16x16x32_bf16(kf[jj][kt][1], qf[jj][1], a, 0, 0, 0); }
;             u32x4 pw[2];
; #pragma unroll
;             for (int jj = 0; jj < 2; ++jj) {
;                 const float tm = vmax3(vmax3(s[jj][0][0], s[jj][0][1], s[jj][0][2]), vmax3(s[jj][0][3], s[jj][1][0], s[jj][1][1]), vmax3(s[jj][1][2], s[jj][1][3], s[jj][1][3]));
;                 const float mn = quad_max3(mrun[jj], tm);
;                 const float alpha = __builtin_amdgcn_exp2f(mrun[jj] - mn);
;                 mrun[jj] = mn;
;                 float rsum = 0.f;
.LBB0_343:
	s_add_i32 s0, s86, s65
	s_mul_hi_i32 s14, s0, 0x55555556
	s_lshr_b32 s15, s14, 31
	s_add_i32 s14, s14, s15
	s_mul_i32 s14, s14, 3
	s_sub_i32 s0, s0, s14
	s_lshl_b32 s0, s0, 14
	s_add_i32 s0, s0, 0
	s_add_i32 s14, s27, 31
	s_cmp_lt_i32 s14, s41
	s_cselect_b64 s[50:51], -1, 0
	s_cmp_gt_i32 s27, s45
	s_cselect_b64 s[52:53], -1, 0
	s_or_b64 s[50:51], s[50:51], s[52:53]
	v_add_u32_e32 v0, s0, v78
	s_and_b64 vcc, exec, s[50:51]
	v_add_u32_e32 v98, s0, v70
	v_add_u32_e32 v97, s0, v71
	v_add_u32_e32 v96, s40, v80
	v_add_u32_e32 v85, s40, v79
	v_add_u32_e32 v84, v0, v74
	v_add_u32_e32 v83, v0, v75
	v_add_u32_e32 v81, v0, v76
	v_add_u32_e32 v0, v0, v77
	s_cbranch_vccnz .LBB0_345
	v_add_u32_e32 v2, 0x10000, v96
	v_add_u32_e32 v3, 0x10040, v96
	ds_read_b128 v[100:103], v98
	ds_read_b128 v[104:107], v98 offset:2048
	ds_read_b128 v[108:111], v97
	ds_read_b128 v[112:115], v97 offset:2048
	ds_read_b128 v[118:121], v2
	ds_read_b128 v[122:125], v3
	v_add_u32_e32 v2, 0x10000, v85
	v_add_u32_e32 v3, 0x10040, v85
	ds_read_b128 v[126:129], v2
	ds_read_b128 v[130:133], v3
	ds_read_b64_tr_b16 v[14:15], v84 offset:8192
	ds_read_b64_tr_b16 v[16:17], v84 offset:10240
	ds_read_b64_tr_b16 v[10:11], v83 offset:8192
	ds_read_b64_tr_b16 v[12:13], v83 offset:10240
	ds_read_b64_tr_b16 v[6:7], v81 offset:8192
	ds_read_b64_tr_b16 v[8:9], v81 offset:10240
	ds_read_b64_tr_b16 v[2:3], v0 offset:8192
	ds_read_b64_tr_b16 v[4:5], v0 offset:10240
	s_waitcnt lgkmcnt(11)
	v_mfma_f32_16x16x32_bf16 v[118:121], v[100:103], v[30:33], v[118:121]
	s_waitcnt lgkmcnt(10)
	v_mfma_f32_16x16x32_bf16 v[122:125], v[104:107], v[30:33], v[122:125]
	v_mfma_f32_16x16x32_bf16 v[118:121], v[108:111], v[26:29], v[118:121]
	v_mfma_f32_16x16x32_bf16 v[122:125], v[112:115], v[26:29], v[122:125]
	s_waitcnt lgkmcnt(9)
	v_mfma_f32_16x16x32_bf16 v[100:103], v[100:103], v[22:25], v[126:129]
	s_nop 4
	v_maximum3_f32 v99, v118, v119, v120
	v_mfma_f32_16x16x32_bf16 v[100:103], v[108:111], v[18:21], v[100:103]
	v_maximum3_f32 v108, v121, v122, v123
	v_maximum3_f32 v109, v124, v125, v125
	v_maximum3_f32 v99, v99, v108, v109
	s_waitcnt lgkmcnt(8)
	v_mfma_f32_16x16x32_bf16 v[104:107], v[104:107], v[22:25], v[130:133]
	v_mov_b32_e32 v108, v99
	s_nop 1
	v_permlane16_swap_b32_e32 v99, v108
	v_maximum3_f32 v99, v99, v108, v108
	v_mfma_f32_16x16x32_bf16 v[104:107], v[112:115], v[18:21], v[104:107]
	v_mov_b32_e32 v108, v99
	s_nop 1
	v_permlane32_swap_b32_e32 v99, v108
	v_maximum3_f32 v99, v82, v99, v108
	v_sub_f32_e32 v82, v82, v99
	v_exp_f32_e32 v130, v82
	v_maximum3_f32 v82, v100, v101, v102
	v_maximum3_f32 v113, v103, v104, v105
	v_maximum3_f32 v115, v106, v107, v107
	v_maximum3_f32 v82, v82, v113, v115
	v_mov_b32_e32 v113, v82
	s_nop 1
	v_permlane16_swap_b32_e32 v82, v113
	v_maximum3_f32 v82, v82, v113, v113
	v_mov_b32_e32 v113, v82
	s_nop 1
	v_permlane32_swap_b32_e32 v82, v113
	v_maximum3_f32 v117, v95, v82, v113
	v_sub_f32_e32 v108, v118, v99
	v_sub_f32_e32 v82, v95, v117
	v_sub_f32_e32 v95, v100, v117
	v_exp_f32_e32 v112, v108
	v_sub_f32_e32 v108, v119, v99
	v_exp_f32_e32 v113, v95
	v_sub_f32_e32 v95, v101, v117
	v_exp_f32_e32 v114, v108
	v_sub_f32_e32 v108, v120, v99
	v_exp_f32_e32 v115, v95
	v_sub_f32_e32 v95, v102, v117
	v_exp_f32_e32 v118, v108
	v_sub_f32_e32 v108, v121, v99
	v_exp_f32_e32 v119, v95
	v_sub_f32_e32 v95, v103, v117
	v_exp_f32_e32 v120, v108
	v_sub_f32_e32 v108, v122, v99
	v_exp_f32_e32 v121, v95
	v_sub_f32_e32 v95, v104, v117
	v_exp_f32_e32 v122, v108
	v_sub_f32_e32 v108, v123, v99
	v_exp_f32_e32 v123, v95
	v_sub_f32_e32 v95, v105, v117
	v_pk_add_f32 v[100:101], v[112:113], 0 op_sel_hi:[1,0]
	v_exp_f32_e32 v126, v108
	v_sub_f32_e32 v108, v124, v99
	v_exp_f32_e32 v127, v95
	v_sub_f32_e32 v95, v106, v117
	v_pk_add_f32 v[100:101], v[114:115], v[100:101]
	v_exp_f32_e32 v124, v108
	v_sub_f32_e32 v108, v125, v99
	v_exp_f32_e32 v125, v95
	v_sub_f32_e32 v95, v107, v117
	v_pk_add_f32 v[100:101], v[118:119], v[100:101]
	v_exp_f32_e32 v128, v108
	v_pk_mul_f32 v[52:53], v[52:53], v[130:131] op_sel_hi:[1,0]
	v_pk_mul_f32 v[50:51], v[50:51], v[130:131] op_sel_hi:[1,0]
	v_pk_mul_f32 v[56:57], v[56:57], v[130:131] op_sel_hi:[1,0]
	v_pk_mul_f32 v[54:55], v[54:55], v[130:131] op_sel_hi:[1,0]
	v_pk_mul_f32 v[60:61], v[60:61], v[130:131] op_sel_hi:[1,0]
	v_pk_mul_f32 v[58:59], v[58:59], v[130:131] op_sel_hi:[1,0]
	v_pk_mul_f32 v[64:65], v[64:65], v[130:131] op_sel_hi:[1,0]
	v_pk_mul_f32 v[62:63], v[62:63], v[130:131] op_sel_hi:[1,0]
	v_exp_f32_e32 v129, v95
	v_pk_add_f32 v[100:101], v[120:121], v[100:101]
	v_exp_f32_e32 v131, v82
	v_pk_add_f32 v[100:101], v[122:123], v[100:101]
	v_cvt_pk_bf16_f32 v108, v112, v114
	v_pk_add_f32 v[100:101], v[126:127], v[100:101]
	v_mov_b32_e32 v82, v131
	v_pk_add_f32 v[100:101], v[124:125], v[100:101]
	v_cvt_pk_bf16_f32 v109, v118, v120
	v_pk_add_f32 v[100:101], v[128:129], v[100:101]
	v_cvt_pk_bf16_f32 v110, v122, v126
	v_cvt_pk_bf16_f32 v111, v124, v128
	v_pk_fma_f32 v[88:89], v[88:89], v[130:131], v[100:101]
	v_pk_mul_f32 v[36:37], v[36:37], v[82:83] op_sel_hi:[1,0]
	v_pk_mul_f32 v[34:35], v[34:35], v[82:83] op_sel_hi:[1,0]
	v_pk_mul_f32 v[40:41], v[40:41], v[82:83] op_sel_hi:[1,0]
	v_pk_mul_f32 v[38:39], v[38:39], v[82:83] op_sel_hi:[1,0]
	v_pk_mul_f32 v[44:45], v[44:45], v[82:83] op_sel_hi:[1,0]
	v_pk_mul_f32 v[42:43], v[42:43], v[82:83] op_sel_hi:[1,0]
	v_pk_mul_f32 v[48:49], v[48:49], v[82:83] op_sel_hi:[1,0]
	v_pk_mul_f32 v[46:47], v[46:47], v[82:83] op_sel_hi:[1,0]
	v_cvt_pk_bf16_f32 v100, v113, v115
	v_cvt_pk_bf16_f32 v101, v119, v121
	v_cvt_pk_bf16_f32 v102, v123, v127
	v_cvt_pk_bf16_f32 v103, v125, v129
	s_waitcnt lgkmcnt(0)
	v_mfma_f32_16x16x32_bf16 v[50:53], v[14:17], v[108:111], v[50:53]
	v_mfma_f32_16x16x32_bf16 v[54:57], v[10:13], v[108:111], v[54:57]
	v_mfma_f32_16x16x32_bf16 v[58:61], v[6:9], v[108:111], v[58:61]
	v_mfma_f32_16x16x32_bf16 v[62:65], v[2:5], v[108:111], v[62:65]
	v_mfma_f32_16x16x32_bf16 v[34:37], v[14:17], v[100:103], v[34:37]
	v_mfma_f32_16x16x32_bf16 v[38:41], v[10:13], v[100:103], v[38:41]
	v_mfma_f32_16x16x32_bf16 v[42:45], v[6:9], v[100:103], v[42:45]
	v_mfma_f32_16x16x32_bf16 v[46:49], v[2:5], v[100:103], v[46:49]
	v_mov_b32_e32 v82, v99
	v_mov_b32_e32 v95, v117
; template <int MODE> ...
;     ...
;         for (int hf = 0; hf < NH; ++hf) {
;             if (MODE == 1) { const int ks = ktok0 + 64 * t + 32 * hf;
;                 if (ks + 31 < qtok0 - 128 || ks > qtok0 + 31 + 128) continue; }
;             bf16x8 kf[2][2][2];
; #pragma unroll
;             for (int jj = 0; jj < 2; ++jj)
; #pragma unroll
;                 for (int kt = 0; kt < 2; ++kt)
; #pragma unroll
;                     for (int ks = 0; ks < 2; ++ks) kf[jj][kt][ks] = *(const LAS bf16x8*)(Sl + kad[jj][ks] + (32 * hf + 16 * kt) * 128);
;             f32x4 bb[2][2];
; #pragma unroll
;             for (int jj = 0; jj < 2; ++jj) { const LAS f32x4* bl = bcp + ((MODE == 0) ? (dr0 + t - act0) * 8 : 16 * t + 8 * hf) + bofs[jj];
; #pragma unroll
;                 for (int kt = 0; kt < 2; ++kt) bb[jj][kt] = bl[4 * kt]; }
;             s16x4 vlo[2][4], vhi[2][4];
; #pragma unroll
;             for (int jj = 0; jj < 2; ++jj)
; #pragma unroll
;                 for (int dt = 0; dt < 4; ++dt) { const LAS unsigned char* vp = Sl + vad[jj] + (32 * hf) * 128 + ((dt ^ sv) << 5);
;                     vlo[jj][dt] = __builtin_bit_cast(s16x4, __builtin_amdgcn_ds_read_tr16_b64_v4i16((LAS s16x4*)(vp)));
;                     vhi[jj][dt] = __builtin_bit_cast(s16x4, __builtin_amdgcn_ds_read_tr16_b64_v4i16((LAS s16x4*)(vp + 2048))); }
;             __builtin_amdgcn_sched_barrier(0);
;             f32x4 s[2][2];
; #pragma unroll
;             for (int jj = 0; jj < 2; ++jj)
; #pragma unroll
;                 for (int kt = 0; kt < 2; ++kt) { f32x4 a = (MODE == 0) ? bb[jj][kt] + mneg[jj][kt] : bb[jj][kt];
;                     a = __builtin_amdgcn_mfma_f32_16x16x32_bf16(kf[jj][kt][0], qf[jj][0], a, 0, 0, 0);
;                     s[jj][kt] = __builtin_amdgcn_mfma_f32_16x16x32_bf16(kf[jj][kt][1], qf[jj][1], a, 0, 0, 0); }
;             u32x4 pw[2];
; #pragma unroll
;             for (int jj = 0; jj < 2; ++jj) {
;                 const float tm = vmax3(vmax3(s[jj][0][0], s[jj][0][1], s[jj][0][2]), vmax3(s[jj][0][3], s[jj][1][0], s[jj][1][1]), vmax3(s[jj][1][2], s[jj][1][3], s[jj][1][3]));
;                 const float mn = quad_max3(mrun[jj], tm);
;                 const float alpha = __builtin_amdgcn_exp2f(mrun[jj] - mn);
;                 mrun[jj] = mn;
;                 float rsum = 0.f;
; #pragma unroll
;                 for (int kt = 0; kt < 2; ++kt)
; #pragma unroll
.LBB0_345:
	s_add_i32 s0, s27, 32
	s_add_i32 s14, s27, 63
	s_cmp_lt_i32 s14, s41
	s_cselect_b64 s[50:51], -1, 0
	s_cmp_gt_i32 s0, s45
	s_cselect_b64 s[52:53], -1, 0
	s_or_b64 s[50:51], s[50:51], s[52:53]
	s_and_b64 vcc, exec, s[50:51]
	s_cbranch_vccnz .LBB0_333
	v_add_u32_e32 v2, 0x10080, v96
	v_add_u32_e32 v3, 0x100c0, v96
	ds_read_b128 v[100:103], v98 offset:4096
	ds_read_b128 v[104:107], v98 offset:6144
	ds_read_b128 v[108:111], v97 offset:4096
	ds_read_b128 v[112:115], v97 offset:6144
	ds_read_b128 v[96:99], v2
	ds_read_b128 v[118:121], v3
	v_add_u32_e32 v2, 0x10080, v85
	v_add_u32_e32 v3, 0x100c0, v85
	ds_read_b128 v[122:125], v2
	ds_read_b128 v[126:129], v3
	ds_read_b64_tr_b16 v[14:15], v84 offset:12288
	ds_read_b64_tr_b16 v[16:17], v84 offset:14336
	ds_read_b64_tr_b16 v[10:11], v83 offset:12288
	ds_read_b64_tr_b16 v[12:13], v83 offset:14336
	ds_read_b64_tr_b16 v[6:7], v81 offset:12288
	ds_read_b64_tr_b16 v[8:9], v81 offset:14336
	ds_read_b64_tr_b16 v[2:3], v0 offset:12288
	ds_read_b64_tr_b16 v[4:5], v0 offset:14336
	s_waitcnt lgkmcnt(11)
	v_mfma_f32_16x16x32_bf16 v[96:99], v[100:103], v[30:33], v[96:99]
	s_waitcnt lgkmcnt(10)
	v_mfma_f32_16x16x32_bf16 v[118:121], v[104:107], v[30:33], v[118:121]
	v_mfma_f32_16x16x32_bf16 v[96:99], v[108:111], v[26:29], v[96:99]
	v_mfma_f32_16x16x32_bf16 v[118:121], v[112:115], v[26:29], v[118:121]
	s_waitcnt lgkmcnt(9)
	v_mfma_f32_16x16x32_bf16 v[100:103], v[100:103], v[22:25], v[122:125]
	s_nop 4
	v_maximum3_f32 v0, v96, v97, v98
	v_maximum3_f32 v81, v99, v118, v119
	v_maximum3_f32 v83, v120, v121, v121
	v_maximum3_f32 v0, v0, v81, v83
	v_mov_b32_e32 v81, v0
	s_waitcnt lgkmcnt(8)
	v_mfma_f32_16x16x32_bf16 v[104:107], v[104:107], v[22:25], v[126:129]
	v_permlane16_swap_b32_e32 v0, v81
	v_maximum3_f32 v0, v0, v81, v81
	v_mov_b32_e32 v81, v0
	s_nop 1
	v_permlane32_swap_b32_e32 v0, v81
	v_mfma_f32_16x16x32_bf16 v[100:103], v[108:111], v[18:21], v[100:103]
	v_maximum3_f32 v81, v82, v0, v81
	v_sub_f32_e32 v0, v82, v81
	v_sub_f32_e32 v82, v96, v81
	v_mfma_f32_16x16x32_bf16 v[104:107], v[112:115], v[18:21], v[104:107]
	v_exp_f32_e32 v96, v82
	v_sub_f32_e32 v82, v97, v81
	v_exp_f32_e32 v108, v82
	v_sub_f32_e32 v82, v98, v81
	v_exp_f32_e32 v98, v82
	v_sub_f32_e32 v82, v99, v81
	v_exp_f32_e32 v122, v0
	v_maximum3_f32 v0, v100, v101, v102
	v_maximum3_f32 v97, v103, v104, v105
	v_maximum3_f32 v99, v106, v107, v107
	v_maximum3_f32 v0, v0, v97, v99
	v_mov_b32_e32 v97, v0
	s_nop 1
	v_permlane16_swap_b32_e32 v0, v97
	v_maximum3_f32 v0, v0, v97, v97
	v_mov_b32_e32 v97, v0
	s_nop 1
	v_permlane32_swap_b32_e32 v0, v97
	v_maximum3_f32 v117, v95, v0, v97
	v_sub_f32_e32 v0, v95, v117
	v_sub_f32_e32 v95, v100, v117
	v_exp_f32_e32 v97, v95
	v_sub_f32_e32 v95, v101, v117
	v_exp_f32_e32 v109, v95
	v_sub_f32_e32 v95, v102, v117
	v_exp_f32_e32 v99, v95
	v_sub_f32_e32 v95, v103, v117
	v_exp_f32_e32 v110, v82
	v_sub_f32_e32 v82, v118, v81
	v_exp_f32_e32 v111, v95
	v_sub_f32_e32 v95, v104, v117
	v_exp_f32_e32 v112, v82
	v_sub_f32_e32 v82, v119, v81
	v_exp_f32_e32 v113, v95
	v_sub_f32_e32 v95, v105, v117
	v_exp_f32_e32 v114, v82
	v_sub_f32_e32 v82, v120, v81
	v_exp_f32_e32 v115, v95
	v_sub_f32_e32 v95, v106, v117
	v_exp_f32_e32 v118, v82
	v_sub_f32_e32 v82, v121, v81
	v_pk_mul_f32 v[52:53], v[52:53], v[122:123] op_sel_hi:[1,0]
	v_pk_mul_f32 v[50:51], v[50:51], v[122:123] op_sel_hi:[1,0]
	v_pk_mul_f32 v[56:57], v[56:57], v[122:123] op_sel_hi:[1,0]
	v_pk_mul_f32 v[54:55], v[54:55], v[122:123] op_sel_hi:[1,0]
	v_pk_mul_f32 v[60:61], v[60:61], v[122:123] op_sel_hi:[1,0]
	v_pk_mul_f32 v[58:59], v[58:59], v[122:123] op_sel_hi:[1,0]
	v_pk_mul_f32 v[64:65], v[64:65], v[122:123] op_sel_hi:[1,0]
	v_pk_mul_f32 v[62:63], v[62:63], v[122:123] op_sel_hi:[1,0]
	v_exp_f32_e32 v119, v95
	v_sub_f32_e32 v95, v107, v117
	v_exp_f32_e32 v123, v0
	v_exp_f32_e32 v120, v82
	v_pk_add_f32 v[100:101], v[96:97], 0 op_sel_hi:[1,0]
	v_exp_f32_e32 v121, v95
	v_pk_add_f32 v[100:101], v[108:109], v[100:101]
	v_mov_b32_e32 v0, v123
	v_pk_add_f32 v[100:101], v[98:99], v[100:101]
	v_cvt_pk_bf16_f32 v82, v96, v108
	v_pk_add_f32 v[100:101], v[110:111], v[100:101]
	v_cvt_pk_bf16_f32 v83, v98, v110
	v_cvt_pk_bf16_f32 v84, v112, v114
	v_cvt_pk_bf16_f32 v85, v118, v120
	v_pk_add_f32 v[100:101], v[112:113], v[100:101]
	v_pk_mul_f32 v[36:37], v[36:37], v[0:1] op_sel_hi:[1,0]
	v_pk_mul_f32 v[34:35], v[34:35], v[0:1] op_sel_hi:[1,0]
	v_pk_mul_f32 v[40:41], v[40:41], v[0:1] op_sel_hi:[1,0]
	v_pk_mul_f32 v[38:39], v[38:39], v[0:1] op_sel_hi:[1,0]
	v_pk_mul_f32 v[44:45], v[44:45], v[0:1] op_sel_hi:[1,0]
	v_pk_mul_f32 v[42:43], v[42:43], v[0:1] op_sel_hi:[1,0]
	v_pk_mul_f32 v[48:49], v[48:49], v[0:1] op_sel_hi:[1,0]
	v_pk_mul_f32 v[46:47], v[46:47], v[0:1] op_sel_hi:[1,0]
	v_cvt_pk_bf16_f32 v96, v97, v109
	v_cvt_pk_bf16_f32 v97, v99, v111
	v_cvt_pk_bf16_f32 v98, v113, v115
	v_cvt_pk_bf16_f32 v99, v119, v121
	v_pk_add_f32 v[100:101], v[114:115], v[100:101]
	s_waitcnt lgkmcnt(0)
	v_mfma_f32_16x16x32_bf16 v[50:53], v[14:17], v[82:85], v[50:53]
	v_pk_add_f32 v[100:101], v[118:119], v[100:101]
	v_pk_add_f32 v[100:101], v[120:121], v[100:101]
	v_mfma_f32_16x16x32_bf16 v[54:57], v[10:13], v[82:85], v[54:57]
	v_fma_f32 v88, v88, v122, v100
	v_fma_f32 v89, v89, v123, v101
	v_mfma_f32_16x16x32_bf16 v[58:61], v[6:9], v[82:85], v[58:61]
	v_mfma_f32_16x16x32_bf16 v[62:65], v[2:5], v[82:85], v[62:65]
	v_mfma_f32_16x16x32_bf16 v[34:37], v[14:17], v[96:99], v[34:37]
	v_mfma_f32_16x16x32_bf16 v[38:41], v[10:13], v[96:99], v[38:41]
	v_mfma_f32_16x16x32_bf16 v[42:45], v[6:9], v[96:99], v[42:45]
	v_mfma_f32_16x16x32_bf16 v[46:49], v[2:5], v[96:99], v[46:49]
	v_mov_b32_e32 v95, v117
	v_mov_b32_e32 v82, v81
	s_branch .LBB0_333

; template <int MODE> ...
;     ...
;         if (t >= act0 && t < act0 + actn) {
;         const LAS unsigned char* Sl = ring + ((t + base) % 3) * SLOT;
; #pragma unroll
;         for (int hf = 0; hf < NH; ++hf) {
;             if (MODE == 1) { const int ks = ktok0 + 64 * t + 32 * hf;
;                 if (ks + 31 < qtok0 - 128 || ks > qtok0 + 31 + 128) continue; }
;             bf16x8 kf[2][2][2];
; #pragma unroll
;             for (int jj = 0; jj < 2; ++jj)
; #pragma unroll
;                 for (int kt = 0; kt < 2; ++kt)
; #pragma unroll
;                     for (int ks = 0; ks < 2; ++ks) kf[jj][kt][ks] = *(const LAS bf16x8*)(Sl + kad[jj][ks] + (32 * hf + 16 * kt) * 128);
;             f32x4 bb[2][2];
; #pragma unroll
;             for (int jj = 0; jj < 2; ++jj) { const LAS f32x4* bl = bcp + ((MODE == 0) ? (dr0 + t - act0) * 8 : 16 * t + 8 * hf) + bofs[jj];
; #pragma unroll
;                 for (int kt = 0; kt < 2; ++kt) bb[jj][kt] = bl[4 * kt]; }
;             s16x4 vlo[2][4], vhi[2][4];
; #pragma unroll
;             for (int jj = 0; jj < 2; ++jj)
; #pragma unroll
;                 for (int dt = 0; dt < 4; ++dt) { const LAS unsigned char* vp = Sl + vad[jj] + (32 * hf) * 128 + ((dt ^ sv) << 5);
;                     vlo[jj][dt] = __builtin_bit_cast(s16x4, __builtin_amdgcn_ds_read_tr16_b64_v4i16((LAS s16x4*)(vp)));
;                     vhi[jj][dt] = __builtin_bit_cast(s16x4, __builtin_amdgcn_ds_read_tr16_b64_v4i16((LAS s16x4*)(vp + 2048))); }
;             __builtin_amdgcn_sched_barrier(0);
;             f32x4 s[2][2];
; #pragma unroll
;             for (int jj = 0; jj < 2; ++jj)
; #pragma unroll
;                 for (int kt = 0; kt < 2; ++kt) { f32x4 a = (MODE == 0) ? bb[jj][kt] + mneg[jj][kt] : bb[jj][kt];
;                     a = __builtin_amdgcn_mfma_f32_16x16x32_bf16(kf[jj][kt][0], qf[jj][0], a, 0, 0, 0);
;                     s[jj][kt] = __builtin_amdgcn_mfma_f32_16x16x32_bf16(kf[jj][kt][1], qf[jj][1], a, 0, 0, 0); }
;             u32x4 pw[2];
; #pragma unroll
;             for (int jj = 0; jj < 2; ++jj) {
;     ...
;     { const GAS bf16_t* qs = nQ ? (const GAS bf16_t*)nQ : (const GAS bf16_t*)proj + (size_t)qtok0 * NIN + qcol;
; #pragma unroll
;       for (int jj = 0; jj < 2; ++jj)
; #pragma unroll
;           for (int ks = 0; ks < 2; ++ks) qn[jj][ks] = *(const GAS bf16x8*)(qs + (size_t)(16 * jj) * NIN + 32 * ks + qoff); }
.LBB0_356:
	v_lshl_add_u64 v[6:7], v[66:67], 1, s[38:39]
	global_load_dwordx4 v[2:5], v[6:7], off
	global_load_dwordx4 v[10:13], v[6:7], off offset:64
	v_add_co_u32_e32 v6, vcc, 0x12000, v6
	s_cmp_lt_i32 s5, 1
	s_nop 0
	v_addc_co_u32_e32 v7, vcc, 0, v7, vcc
	global_load_dwordx4 v[14:17], v[6:7], off
	s_nop 0
	global_load_dwordx4 v[6:9], v[6:7], off offset:64
	s_cbranch_scc1 .LBB0_361
	s_mul_i32 s0, s22, 0x600
	s_add_i32 s27, s0, 0
	s_add_i32 s0, s26, s86
	s_mul_hi_i32 s14, s0, 0x55555556
	s_lshr_b32 s15, s14, 31
	s_add_i32 s14, s14, s15
	s_mul_i32 s14, s14, 3
	s_sub_i32 s0, s0, s14
	s_lshl_b32 s30, s26, 6
	s_lshl_b32 s0, s0, 14
	s_add_i32 s14, s30, s24
	s_add_i32 s27, s27, 0x10000
	s_add_i32 s0, s0, 0
	s_lshl_b32 s26, s26, 8
	s_or_b32 s15, s14, 31
	s_add_i32 s31, s25, 0xffffff80
	s_cmp_lt_i32 s15, s31
	s_cselect_b64 s[38:39], -1, 0
	s_addk_i32 s25, 0x9f
	s_cmp_gt_i32 s14, s25
	s_cselect_b64 s[40:41], -1, 0
	s_or_b64 s[38:39], s[38:39], s[40:41]
	v_add_u32_e32 v100, s0, v70
	v_add_u32_e32 v99, s0, v71
	v_add3_u32 v66, v72, v73, s0
	s_movk_i32 s0, 0x60
	s_and_b64 vcc, exec, s[38:39]
	v_add_u32_e32 v98, v66, v74
	v_xad_u32 v97, v74, 32, v66
	v_xad_u32 v0, v74, 64, v66
	v_xad_u32 v96, v74, s0, v66
	s_cbranch_vccnz .LBB0_359
	s_add_i32 s0, s27, s26
	v_lshl_add_u32 v66, v93, 4, s0
	ds_read_b128 v[102:105], v100
	ds_read_b128 v[106:109], v100 offset:2048
	ds_read_b128 v[110:113], v99
	ds_read_b128 v[118:121], v99 offset:2048
	ds_read_b128 v[122:125], v66
	ds_read_b128 v[126:129], v66 offset:64
	v_lshl_add_u32 v66, v94, 4, s0
	ds_read_b128 v[130:133], v66
	ds_read_b128 v[134:137], v66 offset:64
	ds_read_b64_tr_b16 v[78:79], v98 offset:8192
	ds_read_b64_tr_b16 v[80:81], v98 offset:10240
	ds_read_b64_tr_b16 v[74:75], v97 offset:8192
	ds_read_b64_tr_b16 v[76:77], v97 offset:10240
	ds_read_b64_tr_b16 v[70:71], v0 offset:8192
	ds_read_b64_tr_b16 v[72:73], v0 offset:10240
	ds_read_b64_tr_b16 v[66:67], v96 offset:8192
	ds_read_b64_tr_b16 v[68:69], v96 offset:10240
	s_waitcnt lgkmcnt(11)
	v_mfma_f32_16x16x32_bf16 v[122:125], v[102:105], v[30:33], v[122:125]
	s_waitcnt lgkmcnt(10)
	v_mfma_f32_16x16x32_bf16 v[126:129], v[106:109], v[30:33], v[126:129]
	s_waitcnt lgkmcnt(9)
	v_mfma_f32_16x16x32_bf16 v[102:105], v[102:105], v[22:25], v[130:133]
	s_waitcnt lgkmcnt(8)
	v_mfma_f32_16x16x32_bf16 v[106:109], v[106:109], v[22:25], v[134:137]
	v_mfma_f32_16x16x32_bf16 v[102:105], v[110:113], v[18:21], v[102:105]
	v_mfma_f32_16x16x32_bf16 v[106:109], v[118:121], v[18:21], v[106:109]
	v_mfma_f32_16x16x32_bf16 v[122:125], v[110:113], v[26:29], v[122:125]
	s_nop 5
	v_maximum3_f32 v111, v102, v103, v104
	v_maximum3_f32 v113, v105, v106, v107
	v_maximum3_f32 v115, v108, v109, v109
	v_mfma_f32_16x16x32_bf16 v[126:129], v[118:121], v[26:29], v[126:129]
	v_maximum3_f32 v111, v111, v113, v115
	v_maximum3_f32 v83, v122, v123, v124
	v_mov_b32_e32 v113, v111
	s_nop 1
	v_permlane16_swap_b32_e32 v111, v113
	v_maximum3_f32 v111, v111, v113, v113
	s_nop 0
	v_maximum3_f32 v84, v125, v126, v127
	v_maximum3_f32 v85, v128, v129, v129
	v_maximum3_f32 v83, v83, v84, v85
	v_mov_b32_e32 v84, v83
	s_nop 1
	v_permlane16_swap_b32_e32 v83, v84
	v_maximum3_f32 v83, v83, v84, v84
	v_mov_b32_e32 v113, v111
	v_mov_b32_e32 v84, v83
	s_nop 0
	v_permlane32_swap_b32_e32 v111, v113
	v_permlane32_swap_b32_e32 v83, v84
	v_maximum3_f32 v117, v95, v111, v113
	v_maximum3_f32 v101, v82, v83, v84
	v_sub_f32_e32 v102, v102, v117
	v_sub_f32_e32 v83, v122, v101
	v_exp_f32_e32 v111, v102
	v_sub_f32_e32 v102, v103, v117
	v_exp_f32_e32 v110, v83
	v_sub_f32_e32 v83, v123, v101
	v_exp_f32_e32 v113, v102
	v_sub_f32_e32 v102, v104, v117
	v_exp_f32_e32 v112, v83
	v_sub_f32_e32 v83, v124, v101
	v_exp_f32_e32 v115, v102
	v_sub_f32_e32 v102, v105, v117
	v_exp_f32_e32 v114, v83
	v_sub_f32_e32 v83, v125, v101
	v_exp_f32_e32 v119, v102
	v_sub_f32_e32 v102, v106, v117
	v_exp_f32_e32 v118, v83
	v_sub_f32_e32 v83, v126, v101
	v_exp_f32_e32 v121, v102
	v_sub_f32_e32 v102, v107, v117
	v_sub_f32_e32 v82, v82, v101
	v_exp_f32_e32 v120, v83
	v_sub_f32_e32 v83, v127, v101
	v_exp_f32_e32 v123, v102
	v_sub_f32_e32 v102, v108, v117
	v_exp_f32_e32 v122, v83
	v_sub_f32_e32 v83, v128, v101
	v_exp_f32_e32 v128, v82
	v_pk_add_f32 v[130:131], v[110:111], 0 op_sel_hi:[1,0]
	v_exp_f32_e32 v125, v102
	v_sub_f32_e32 v102, v109, v117
	v_exp_f32_e32 v127, v102
	v_pk_add_f32 v[102:103], v[112:113], v[130:131]
	v_exp_f32_e32 v124, v83
	v_sub_f32_e32 v83, v129, v101
	v_pk_add_f32 v[102:103], v[114:115], v[102:103]
	v_exp_f32_e32 v126, v83
	v_sub_f32_e32 v95, v95, v117
	v_pk_add_f32 v[102:103], v[118:119], v[102:103]
	v_pk_mul_f32 v[52:53], v[52:53], v[128:129] op_sel_hi:[1,0]
	v_pk_mul_f32 v[50:51], v[50:51], v[128:129] op_sel_hi:[1,0]
	v_pk_mul_f32 v[56:57], v[56:57], v[128:129] op_sel_hi:[1,0]
	v_pk_mul_f32 v[54:55], v[54:55], v[128:129] op_sel_hi:[1,0]
	v_pk_mul_f32 v[60:61], v[60:61], v[128:129] op_sel_hi:[1,0]
	v_pk_mul_f32 v[58:59], v[58:59], v[128:129] op_sel_hi:[1,0]
	v_pk_mul_f32 v[64:65], v[64:65], v[128:129] op_sel_hi:[1,0]
	v_pk_mul_f32 v[62:63], v[62:63], v[128:129] op_sel_hi:[1,0]
	v_exp_f32_e32 v129, v95
	v_pk_add_f32 v[102:103], v[120:121], v[102:103]
	v_cvt_pk_bf16_f32 v82, v110, v112
	v_pk_add_f32 v[102:103], v[122:123], v[102:103]
	v_cvt_pk_bf16_f32 v83, v114, v118
	v_pk_add_f32 v[102:103], v[124:125], v[102:103]
	v_cvt_pk_bf16_f32 v84, v120, v122
	v_pk_add_f32 v[102:103], v[126:127], v[102:103]
	v_cvt_pk_bf16_f32 v85, v124, v126
	v_pk_fma_f32 v[88:89], v[88:89], v[128:129], v[102:103]
	v_mov_b32_e32 v102, v129
	v_pk_mul_f32 v[36:37], v[36:37], v[102:103] op_sel_hi:[1,0]
	v_pk_mul_f32 v[34:35], v[34:35], v[102:103] op_sel_hi:[1,0]
	v_pk_mul_f32 v[40:41], v[40:41], v[102:103] op_sel_hi:[1,0]
	v_pk_mul_f32 v[38:39], v[38:39], v[102:103] op_sel_hi:[1,0]
	v_pk_mul_f32 v[44:45], v[44:45], v[102:103] op_sel_hi:[1,0]
	v_pk_mul_f32 v[42:43], v[42:43], v[102:103] op_sel_hi:[1,0]
	v_pk_mul_f32 v[48:49], v[48:49], v[102:103] op_sel_hi:[1,0]
	v_pk_mul_f32 v[46:47], v[46:47], v[102:103] op_sel_hi:[1,0]
	v_cvt_pk_bf16_f32 v102, v111, v113
	v_cvt_pk_bf16_f32 v103, v115, v119
	v_cvt_pk_bf16_f32 v104, v121, v123
	v_cvt_pk_bf16_f32 v105, v125, v127
	s_waitcnt lgkmcnt(0)
	v_mfma_f32_16x16x32_bf16 v[50:53], v[78:81], v[82:85], v[50:53]
	v_mfma_f32_16x16x32_bf16 v[54:57], v[74:77], v[82:85], v[54:57]
	v_mfma_f32_16x16x32_bf16 v[58:61], v[70:73], v[82:85], v[58:61]
	v_mfma_f32_16x16x32_bf16 v[62:65], v[66:69], v[82:85], v[62:65]
	v_mfma_f32_16x16x32_bf16 v[34:37], v[78:81], v[102:105], v[34:37]
	v_mfma_f32_16x16x32_bf16 v[38:41], v[74:77], v[102:105], v[38:41]
	v_mfma_f32_16x16x32_bf16 v[42:45], v[70:73], v[102:105], v[42:45]
	v_mfma_f32_16x16x32_bf16 v[46:49], v[66:69], v[102:105], v[46:49]
	v_mov_b32_e32 v82, v101
	v_mov_b32_e32 v95, v117
; template <int MODE> ...
;     ...
;         for (int hf = 0; hf < NH; ++hf) {
;             if (MODE == 1) { const int ks = ktok0 + 64 * t + 32 * hf;
;                 if (ks + 31 < qtok0 - 128 || ks > qtok0 + 31 + 128) continue; }
;             bf16x8 kf[2][2][2];
; #pragma unroll
;             for (int jj = 0; jj < 2; ++jj)
; #pragma unroll
;                 for (int kt = 0; kt < 2; ++kt)
; #pragma unroll
;                     for (int ks = 0; ks < 2; ++ks) kf[jj][kt][ks] = *(const LAS bf16x8*)(Sl + kad[jj][ks] + (32 * hf + 16 * kt) * 128);
;             f32x4 bb[2][2];
; #pragma unroll
;             for (int jj = 0; jj < 2; ++jj) { const LAS f32x4* bl = bcp + ((MODE == 0) ? (dr0 + t - act0) * 8 : 16 * t + 8 * hf) + bofs[jj];
; #pragma unroll
;                 for (int kt = 0; kt < 2; ++kt) bb[jj][kt] = bl[4 * kt]; }
;             s16x4 vlo[2][4], vhi[2][4];
; #pragma unroll
;             for (int jj = 0; jj < 2; ++jj)
; #pragma unroll
;                 for (int dt = 0; dt < 4; ++dt) { const LAS unsigned char* vp = Sl + vad[jj] + (32 * hf) * 128 + ((dt ^ sv) << 5);
;                     vlo[jj][dt] = __builtin_bit_cast(s16x4, __builtin_amdgcn_ds_read_tr16_b64_v4i16((LAS s16x4*)(vp)));
;                     vhi[jj][dt] = __builtin_bit_cast(s16x4, __builtin_amdgcn_ds_read_tr16_b64_v4i16((LAS s16x4*)(vp + 2048))); }
;             __builtin_amdgcn_sched_barrier(0);
;             f32x4 s[2][2];
; #pragma unroll
;             for (int jj = 0; jj < 2; ++jj)
; #pragma unroll
;                 for (int kt = 0; kt < 2; ++kt) { f32x4 a = (MODE == 0) ? bb[jj][kt] + mneg[jj][kt] : bb[jj][kt];
;                     a = __builtin_amdgcn_mfma_f32_16x16x32_bf16(kf[jj][kt][0], qf[jj][0], a, 0, 0, 0);
;                     s[jj][kt] = __builtin_amdgcn_mfma_f32_16x16x32_bf16(kf[jj][kt][1], qf[jj][1], a, 0, 0, 0); }
;             u32x4 pw[2];
; #pragma unroll
;             for (int jj = 0; jj < 2; ++jj) {
;                 const float tm = vmax3(vmax3(s[jj][0][0], s[jj][0][1], s[jj][0][2]), vmax3(s[jj][0][3], s[jj][1][0], s[jj][1][1]), vmax3(s[jj][1][2], s[jj][1][3], s[jj][1][3]));
;                 const float mn = quad_max3(mrun[jj], tm);
;                 const float alpha = __builtin_amdgcn_exp2f(mrun[jj] - mn);
;                 mrun[jj] = mn;
;                 float rsum = 0.f;
; #pragma unroll
;                 for (int kt = 0; kt < 2; ++kt)
; #pragma unroll
.LBB0_359:
	s_or_b32 s0, s30, 32
	s_add_i32 s0, s0, s24
	s_or_b32 s14, s0, 31
	s_cmp_lt_i32 s14, s31
	s_cselect_b64 s[30:31], -1, 0
	s_cmp_gt_i32 s0, s25
	s_cselect_b64 s[24:25], -1, 0
	s_or_b64 s[24:25], s[30:31], s[24:25]
	s_and_b64 vcc, exec, s[24:25]
	s_cbranch_vccnz .LBB0_361
	s_add_i32 s27, s27, s26
	v_lshl_add_u32 v83, v93, 4, s27
	ds_read_b128 v[66:69], v100 offset:4096
	ds_read_b128 v[70:73], v100 offset:6144
	ds_read_b128 v[74:77], v99 offset:4096
	ds_read_b128 v[78:81], v99 offset:6144
	ds_read_b128 v[100:103], v83 offset:128
	ds_read_b128 v[104:107], v83 offset:192
	v_lshl_add_u32 v83, v94, 4, s27
	ds_read_b128 v[108:111], v83 offset:128
	ds_read_b128 v[112:115], v83 offset:192
	ds_read_b64_tr_b16 v[118:119], v98 offset:12288
	ds_read_b64_tr_b16 v[120:121], v98 offset:14336
	ds_read_b64_tr_b16 v[122:123], v97 offset:12288
	ds_read_b64_tr_b16 v[124:125], v97 offset:14336
	ds_read_b64_tr_b16 v[126:127], v0 offset:12288
	ds_read_b64_tr_b16 v[128:129], v0 offset:14336
	ds_read_b64_tr_b16 v[130:131], v96 offset:12288
	ds_read_b64_tr_b16 v[132:133], v96 offset:14336
	s_waitcnt lgkmcnt(11)
	v_mfma_f32_16x16x32_bf16 v[96:99], v[66:69], v[30:33], v[100:103]
	s_waitcnt lgkmcnt(10)
	v_mfma_f32_16x16x32_bf16 v[30:33], v[70:73], v[30:33], v[104:107]
	v_mfma_f32_16x16x32_bf16 v[96:99], v[74:77], v[26:29], v[96:99]
	v_mfma_f32_16x16x32_bf16 v[26:29], v[78:81], v[26:29], v[30:33]
	s_nop 6
	v_maximum3_f32 v0, v96, v97, v98
	v_maximum3_f32 v30, v99, v26, v27
	v_maximum3_f32 v31, v28, v29, v29
	v_maximum3_f32 v0, v0, v30, v31
	v_mov_b32_e32 v30, v0
	s_nop 1
	v_permlane16_swap_b32_e32 v0, v30
	v_maximum3_f32 v0, v0, v30, v30
	v_mov_b32_e32 v30, v0
	s_nop 1
	v_permlane32_swap_b32_e32 v0, v30
	v_maximum3_f32 v0, v82, v0, v30
	s_waitcnt lgkmcnt(9)
	v_mfma_f32_16x16x32_bf16 v[30:33], v[66:69], v[22:25], v[108:111]
	v_sub_f32_e32 v83, v82, v0
	v_sub_f32_e32 v66, v97, v0
	v_exp_f32_e32 v84, v66
	s_waitcnt lgkmcnt(8)
	v_mfma_f32_16x16x32_bf16 v[22:25], v[70:73], v[22:25], v[112:115]
	v_sub_f32_e32 v66, v98, v0
	v_sub_f32_e32 v82, v96, v0
	v_sub_f32_e32 v26, v26, v0
	v_mfma_f32_16x16x32_bf16 v[30:33], v[74:77], v[18:21], v[30:33]
	v_exp_f32_e32 v74, v66
	v_sub_f32_e32 v66, v99, v0
	v_exp_f32_e32 v82, v82
	v_mfma_f32_16x16x32_bf16 v[18:21], v[78:81], v[18:21], v[22:25]
	v_exp_f32_e32 v78, v83
	v_exp_f32_e32 v70, v66
	v_exp_f32_e32 v72, v26
	v_sub_f32_e32 v22, v27, v0
	v_exp_f32_e32 v76, v22
	v_sub_f32_e32 v22, v28, v0
	v_sub_f32_e32 v0, v29, v0
	v_exp_f32_e32 v80, v22
	v_exp_f32_e32 v94, v0
	v_pk_mul_f32 v[22:23], v[50:51], v[78:79] op_sel_hi:[1,0]
	v_maximum3_f32 v0, v30, v31, v32
	v_maximum3_f32 v50, v33, v18, v19
	v_maximum3_f32 v51, v20, v21, v21
	v_maximum3_f32 v0, v0, v50, v51
	v_mov_b32_e32 v50, v0
	s_nop 1
	v_permlane16_swap_b32_e32 v0, v50
	v_maximum3_f32 v0, v0, v50, v50
	v_mov_b32_e32 v50, v0
	s_nop 1
	v_permlane32_swap_b32_e32 v0, v50
	v_maximum3_f32 v0, v95, v0, v50
	v_sub_f32_e32 v30, v30, v0
	v_exp_f32_e32 v83, v30
	v_sub_f32_e32 v30, v31, v0
	v_exp_f32_e32 v85, v30
	v_sub_f32_e32 v30, v32, v0
	v_sub_f32_e32 v18, v18, v0
	v_exp_f32_e32 v75, v30
	v_sub_f32_e32 v30, v33, v0
	v_exp_f32_e32 v73, v18
	v_sub_f32_e32 v18, v19, v0
	v_sub_f32_e32 v50, v95, v0
	v_exp_f32_e32 v71, v30
	v_exp_f32_e32 v77, v18
	v_sub_f32_e32 v18, v20, v0
	v_pk_mul_f32 v[24:25], v[52:53], v[78:79] op_sel_hi:[1,0]
	v_pk_mul_f32 v[28:29], v[56:57], v[78:79] op_sel_hi:[1,0]
	v_pk_mul_f32 v[26:27], v[54:55], v[78:79] op_sel_hi:[1,0]
	v_pk_mul_f32 v[60:61], v[60:61], v[78:79] op_sel_hi:[1,0]
	v_pk_mul_f32 v[58:59], v[58:59], v[78:79] op_sel_hi:[1,0]
	v_pk_mul_f32 v[64:65], v[64:65], v[78:79] op_sel_hi:[1,0]
	v_pk_mul_f32 v[62:63], v[62:63], v[78:79] op_sel_hi:[1,0]
	v_exp_f32_e32 v81, v18
	v_sub_f32_e32 v0, v21, v0
	v_exp_f32_e32 v79, v50
	v_pk_add_f32 v[18:19], v[82:83], 0 op_sel_hi:[1,0]
	v_exp_f32_e32 v95, v0
	v_pk_add_f32 v[18:19], v[84:85], v[18:19]
	v_cvt_pk_bf16_f32 v66, v82, v84
	v_pk_add_f32 v[18:19], v[74:75], v[18:19]
	v_cvt_pk_bf16_f32 v67, v74, v70
	v_pk_add_f32 v[18:19], v[70:71], v[18:19]
	v_cvt_pk_bf16_f32 v68, v72, v76
	v_cvt_pk_bf16_f32 v69, v80, v94
	v_pk_add_f32 v[18:19], v[72:73], v[18:19]
	v_mov_b32_e32 v0, v79
	s_waitcnt lgkmcnt(0)
	v_mfma_f32_16x16x32_bf16 v[50:53], v[118:121], v[66:69], v[22:25]
	v_pk_mul_f32 v[20:21], v[36:37], v[0:1] op_sel_hi:[1,0]
	v_mfma_f32_16x16x32_bf16 v[54:57], v[122:125], v[66:69], v[26:29]
	v_cvt_pk_bf16_f32 v22, v83, v85
	v_cvt_pk_bf16_f32 v23, v75, v71
	v_cvt_pk_bf16_f32 v24, v73, v77
	v_pk_add_f32 v[26:27], v[76:77], v[18:19]
	v_pk_mul_f32 v[18:19], v[34:35], v[0:1] op_sel_hi:[1,0]
	v_cvt_pk_bf16_f32 v25, v81, v95
	v_mfma_f32_16x16x32_bf16 v[58:61], v[126:129], v[66:69], v[58:61]
	v_pk_add_f32 v[26:27], v[80:81], v[26:27]
	v_pk_add_f32 v[26:27], v[94:95], v[26:27]
	v_mfma_f32_16x16x32_bf16 v[34:37], v[118:121], v[22:25], v[18:21]
	v_fma_f32 v88, v88, v78, v26
	v_fma_f32 v89, v89, v79, v27
	s_nop 0
	v_pk_mul_f32 v[20:21], v[40:41], v[0:1] op_sel_hi:[1,0]
	v_pk_mul_f32 v[18:19], v[38:39], v[0:1] op_sel_hi:[1,0]
	v_mfma_f32_16x16x32_bf16 v[62:65], v[130:133], v[66:69], v[62:65]
	v_mfma_f32_16x16x32_bf16 v[38:41], v[122:125], v[22:25], v[18:21]
	s_nop 2
	v_pk_mul_f32 v[20:21], v[44:45], v[0:1] op_sel_hi:[1,0]
	v_pk_mul_f32 v[18:19], v[42:43], v[0:1] op_sel_hi:[1,0]
	s_nop 1
	v_mfma_f32_16x16x32_bf16 v[42:45], v[126:129], v[22:25], v[18:21]
	s_nop 2
	v_pk_mul_f32 v[20:21], v[48:49], v[0:1] op_sel_hi:[1,0]
	v_pk_mul_f32 v[18:19], v[46:47], v[0:1] op_sel_hi:[1,0]
	s_nop 1
	v_mfma_f32_16x16x32_bf16 v[46:49], v[130:133], v[22:25], v[18:21]
